# MFMA order: both 16-MFMA blocks of a compute segment scheduled as one 32-MFMA run (inner setprio pair dropped), chains adjacent, grouped by B fragment
# speedup vs baseline: 1.0550x; 1.0019x over previous
.LBB0_120:
	s_and_b64 vcc, exec, s[6:7]
	s_cbranch_vccz .LBB0_122
	s_waitcnt lgkmcnt(0)
	ds_read_b128 v[4:7], v151
	ds_read_b128 v[8:11], v151 offset:1024
	ds_read_b128 v[12:15], v151 offset:2048
	ds_read_b128 v[16:19], v151 offset:3072
	ds_read_b128 v[20:23], v152
	ds_read_b128 v[24:27], v152 offset:1024
	ds_read_b128 v[28:31], v152 offset:2048
	ds_read_b128 v[32:35], v152 offset:3072
	s_or_b32 s9, s11, 0x100
	s_or_b32 s3, s11, 0x80180
	s_or_b32 s6, s10, 0x80100
	s_or_b32 s7, s11, 0x80100
	s_or_b32 s8, s11, 0x180
	s_or_b32 s12, s10, 0x100
	ds_read_b128 v[36:39], v153
	ds_read_b128 v[40:43], v153 offset:1024
	ds_read_b128 v[44:47], v153 offset:2048
	ds_read_b128 v[48:51], v153 offset:3072
	ds_read_b128 v[52:55], v153 offset:4096
	ds_read_b128 v[56:59], v153 offset:5120
	ds_read_b128 v[60:63], v153 offset:6144
	ds_read_b128 v[64:67], v153 offset:7168
	s_waitcnt vmcnt(24)
	s_waitcnt lgkmcnt(0)
	s_barrier
	s_setprio 1
	s_waitcnt lgkmcnt(1)
	v_mfma_f32_16x16x32_bf16 v[92:95], v[4:7], v[60:63], 0
	v_mfma_f32_16x16x32_bf16 v[68:71], v[4:7], v[36:39], 0
	v_mfma_f32_16x16x32_bf16 v[72:75], v[12:15], v[36:39], 0
	v_mfma_f32_16x16x32_bf16 v[76:79], v[4:7], v[44:47], 0
	v_mfma_f32_16x16x32_bf16 v[80:83], v[12:15], v[44:47], 0
	v_mfma_f32_16x16x32_bf16 v[84:87], v[4:7], v[52:55], 0
	v_mfma_f32_16x16x32_bf16 v[88:91], v[12:15], v[52:55], 0
	s_waitcnt lgkmcnt(0)
	v_mfma_f32_16x16x32_bf16 v[102:105], v[8:11], v[64:67], v[92:95]
	v_mfma_f32_16x16x32_bf16 v[92:95], v[12:15], v[60:63], 0
	v_mfma_f32_16x16x32_bf16 v[68:71], v[8:11], v[40:43], v[68:71]
	v_mfma_f32_16x16x32_bf16 v[76:79], v[8:11], v[48:51], v[76:79]
	v_mfma_f32_16x16x32_bf16 v[84:87], v[8:11], v[56:59], v[84:87]
	v_mfma_f32_16x16x32_bf16 v[72:75], v[16:19], v[40:43], v[72:75]
	v_mfma_f32_16x16x32_bf16 v[80:83], v[16:19], v[48:51], v[80:83]
	v_mfma_f32_16x16x32_bf16 v[88:91], v[16:19], v[56:59], v[88:91]
	v_mfma_f32_16x16x32_bf16 v[106:109], v[16:19], v[64:67], v[92:95]
	v_mfma_f32_16x16x32_bf16 v[92:95], v[20:23], v[36:39], 0
	v_mfma_f32_16x16x32_bf16 v[36:39], v[28:31], v[36:39], 0
	v_mfma_f32_16x16x32_bf16 v[118:121], v[24:27], v[40:43], v[92:95]
	v_mfma_f32_16x16x32_bf16 v[36:39], v[32:35], v[40:43], v[36:39]
	v_mfma_f32_16x16x32_bf16 v[40:43], v[20:23], v[44:47], 0
	v_mfma_f32_16x16x32_bf16 v[44:47], v[28:31], v[44:47], 0
	v_mfma_f32_16x16x32_bf16 v[40:43], v[24:27], v[48:51], v[40:43]
	v_mfma_f32_16x16x32_bf16 v[44:47], v[32:35], v[48:51], v[44:47]
	v_mfma_f32_16x16x32_bf16 v[48:51], v[20:23], v[52:55], 0
	v_mfma_f32_16x16x32_bf16 v[52:55], v[28:31], v[52:55], 0
	v_mfma_f32_16x16x32_bf16 v[48:51], v[24:27], v[56:59], v[48:51]
	v_mfma_f32_16x16x32_bf16 v[52:55], v[32:35], v[56:59], v[52:55]
	v_mfma_f32_16x16x32_bf16 v[56:59], v[20:23], v[60:63], 0
	v_mfma_f32_16x16x32_bf16 v[60:63], v[28:31], v[60:63], 0
	v_mfma_f32_16x16x32_bf16 v[56:59], v[24:27], v[64:67], v[56:59]
	v_mfma_f32_16x16x32_bf16 v[60:63], v[32:35], v[64:67], v[60:63]
	s_setprio 0
	s_barrier
	s_mov_b32 m0, s91
	s_mov_b32 s75, s31
	ds_read_b128 v[64:67], v153 offset:16384
	ds_read_b128 v[92:95], v153 offset:17408
	buffer_load_dwordx4 v146, s[72:75], s9 offen lds
	s_mov_b32 m0, s93
	ds_read_b128 v[96:99], v153 offset:18432
	ds_read_b128 v[110:113], v153 offset:19456
	buffer_load_dwordx4 v148, s[72:75], s9 offen lds
	s_mov_b32 m0, s95
	ds_read_b128 v[114:117], v153 offset:20480
	ds_read_b128 v[122:125], v153 offset:21504
	buffer_load_dwordx4 v146, s[72:75], s7 offen lds
	s_mov_b32 m0, s35
	ds_read_b128 v[126:129], v153 offset:22528
	ds_read_b128 v[130:133], v153 offset:23552
	buffer_load_dwordx4 v148, s[72:75], s7 offen lds
	s_waitcnt vmcnt(22)
	s_waitcnt lgkmcnt(0)
	s_barrier
	s_setprio 1
	s_waitcnt lgkmcnt(7)
	v_mfma_f32_16x16x32_bf16 v[138:141], v[4:7], v[64:67], 0
	s_waitcnt lgkmcnt(5)
	v_mfma_f32_16x16x32_bf16 v[158:161], v[4:7], v[96:99], 0
	s_waitcnt lgkmcnt(3)
	v_mfma_f32_16x16x32_bf16 v[166:169], v[4:7], v[114:117], 0
	s_waitcnt lgkmcnt(1)
	v_mfma_f32_16x16x32_bf16 v[4:7], v[4:7], v[126:129], 0
	s_waitcnt lgkmcnt(0)
	v_mfma_f32_16x16x32_bf16 v[138:141], v[8:11], v[92:95], v[138:141]
	v_mfma_f32_16x16x32_bf16 v[158:161], v[8:11], v[110:113], v[158:161]
	v_mfma_f32_16x16x32_bf16 v[166:169], v[8:11], v[122:125], v[166:169]
	v_mfma_f32_16x16x32_bf16 v[4:7], v[8:11], v[130:133], v[4:7]
	v_mfma_f32_16x16x32_bf16 v[8:11], v[12:15], v[126:129], 0
	v_mfma_f32_16x16x32_bf16 v[142:145], v[12:15], v[64:67], 0
	v_mfma_f32_16x16x32_bf16 v[162:165], v[12:15], v[96:99], 0
	v_mfma_f32_16x16x32_bf16 v[170:173], v[12:15], v[114:117], 0
	v_mfma_f32_16x16x32_bf16 v[8:11], v[16:19], v[130:133], v[8:11]
	v_mfma_f32_16x16x32_bf16 v[142:145], v[16:19], v[92:95], v[142:145]
	v_mfma_f32_16x16x32_bf16 v[162:165], v[16:19], v[110:113], v[162:165]
	v_mfma_f32_16x16x32_bf16 v[170:173], v[16:19], v[122:125], v[170:173]
	v_mfma_f32_16x16x32_bf16 v[12:15], v[20:23], v[64:67], 0
	v_mfma_f32_16x16x32_bf16 v[174:177], v[24:27], v[92:95], v[12:15]
	v_mfma_f32_16x16x32_bf16 v[12:15], v[28:31], v[64:67], 0
	v_mfma_f32_16x16x32_bf16 v[178:181], v[32:35], v[92:95], v[12:15]
	v_mfma_f32_16x16x32_bf16 v[12:15], v[20:23], v[96:99], 0
	v_mfma_f32_16x16x32_bf16 v[182:185], v[24:27], v[110:113], v[12:15]
	v_mfma_f32_16x16x32_bf16 v[12:15], v[28:31], v[96:99], 0
	v_mfma_f32_16x16x32_bf16 v[186:189], v[32:35], v[110:113], v[12:15]
	v_mfma_f32_16x16x32_bf16 v[12:15], v[20:23], v[114:117], 0
	v_mfma_f32_16x16x32_bf16 v[190:193], v[24:27], v[122:125], v[12:15]
	v_mfma_f32_16x16x32_bf16 v[12:15], v[28:31], v[114:117], 0
	v_mfma_f32_16x16x32_bf16 v[194:197], v[32:35], v[122:125], v[12:15]
	v_mfma_f32_16x16x32_bf16 v[12:15], v[20:23], v[126:129], 0
	v_mfma_f32_16x16x32_bf16 v[198:201], v[24:27], v[130:133], v[12:15]
	v_mfma_f32_16x16x32_bf16 v[12:15], v[28:31], v[126:129], 0
	v_mfma_f32_16x16x32_bf16 v[202:205], v[32:35], v[130:133], v[12:15]
	s_setprio 0
	s_barrier
	s_nop 4
	ds_read_b128 v[12:15], v154
	ds_read_b128 v[16:19], v154 offset:1024
	ds_read_b128 v[22:25], v154 offset:2048
	ds_read_b128 v[26:29], v154 offset:3072
	ds_read_b128 v[206:209], v155
	ds_read_b128 v[210:213], v155 offset:1024
	ds_read_b128 v[214:217], v155 offset:2048
	ds_read_b128 v[218:221], v155 offset:3072
	s_mov_b32 m0, s77
	ds_read_b128 v[30:33], v153 offset:32768
	ds_read_b128 v[64:67], v153 offset:33792
	buffer_load_dwordx4 v1, s[28:31], s12 offen lds
	s_mov_b32 m0, s84
	ds_read_b128 v[222:225], v153 offset:34816
	ds_read_b128 v[226:229], v153 offset:35840
	buffer_load_dwordx4 v147, s[28:31], s12 offen lds
	s_mov_b32 m0, s85
	ds_read_b128 v[230:233], v153 offset:36864
	ds_read_b128 v[236:239], v153 offset:37888
	buffer_load_dwordx4 v1, s[28:31], s6 offen lds
	s_mov_b32 m0, s48
	ds_read_b128 v[240:243], v153 offset:38912
	ds_read_b128 v[244:247], v153 offset:39936
	buffer_load_dwordx4 v147, s[28:31], s6 offen lds
	s_waitcnt vmcnt(24)
	s_waitcnt lgkmcnt(0)
	s_barrier
	s_setprio 1
	s_waitcnt lgkmcnt(0)
	v_mfma_f32_16x16x32_bf16 v[68:71], v[12:15], v[30:33], v[68:71]
	v_mfma_f32_16x16x32_bf16 v[130:133], v[16:19], v[64:67], v[68:71]
	v_mfma_f32_16x16x32_bf16 v[68:71], v[22:25], v[30:33], v[72:75]
	v_mfma_f32_16x16x32_bf16 v[126:129], v[26:29], v[64:67], v[68:71]
	v_mfma_f32_16x16x32_bf16 v[68:71], v[12:15], v[222:225], v[76:79]
	v_mfma_f32_16x16x32_bf16 v[114:117], v[16:19], v[226:229], v[68:71]
	v_mfma_f32_16x16x32_bf16 v[68:71], v[22:25], v[222:225], v[80:83]
	v_mfma_f32_16x16x32_bf16 v[110:113], v[26:29], v[226:229], v[68:71]
	v_mfma_f32_16x16x32_bf16 v[68:71], v[12:15], v[230:233], v[84:87]
	v_mfma_f32_16x16x32_bf16 v[98:101], v[16:19], v[236:239], v[68:71]
	v_mfma_f32_16x16x32_bf16 v[68:71], v[22:25], v[230:233], v[88:91]
	v_mfma_f32_16x16x32_bf16 v[94:97], v[26:29], v[236:239], v[68:71]
	v_mfma_f32_16x16x32_bf16 v[68:71], v[12:15], v[240:243], v[102:105]
	v_mfma_f32_16x16x32_bf16 v[82:85], v[16:19], v[244:247], v[68:71]
	v_mfma_f32_16x16x32_bf16 v[68:71], v[22:25], v[240:243], v[106:109]
	v_mfma_f32_16x16x32_bf16 v[78:81], v[26:29], v[244:247], v[68:71]
	v_mfma_f32_16x16x32_bf16 v[68:71], v[206:209], v[30:33], v[118:121]
	v_mfma_f32_16x16x32_bf16 v[122:125], v[210:213], v[64:67], v[68:71]
	v_mfma_f32_16x16x32_bf16 v[30:33], v[214:217], v[30:33], v[36:39]
	v_mfma_f32_16x16x32_bf16 v[118:121], v[218:221], v[64:67], v[30:33]
	v_mfma_f32_16x16x32_bf16 v[30:33], v[206:209], v[222:225], v[40:43]
	v_mfma_f32_16x16x32_bf16 v[106:109], v[210:213], v[226:229], v[30:33]
	v_mfma_f32_16x16x32_bf16 v[30:33], v[214:217], v[222:225], v[44:47]
	v_mfma_f32_16x16x32_bf16 v[102:105], v[218:221], v[226:229], v[30:33]
	v_mfma_f32_16x16x32_bf16 v[30:33], v[206:209], v[230:233], v[48:51]
	v_mfma_f32_16x16x32_bf16 v[90:93], v[210:213], v[236:239], v[30:33]
	v_mfma_f32_16x16x32_bf16 v[30:33], v[214:217], v[230:233], v[52:55]
	v_mfma_f32_16x16x32_bf16 v[86:89], v[218:221], v[236:239], v[30:33]
	v_mfma_f32_16x16x32_bf16 v[30:33], v[206:209], v[240:243], v[56:59]
	v_mfma_f32_16x16x32_bf16 v[74:77], v[210:213], v[244:247], v[30:33]
	v_mfma_f32_16x16x32_bf16 v[30:33], v[214:217], v[240:243], v[60:63]
	v_mfma_f32_16x16x32_bf16 v[70:73], v[218:221], v[244:247], v[30:33]
	s_setprio 0
	s_barrier
	s_mov_b32 m0, s78
	ds_read_b128 v[38:41], v153 offset:49152
	ds_read_b128 v[42:45], v153 offset:50176
	buffer_load_dwordx4 v146, s[72:75], s8 offen lds
	s_mov_b32 m0, s79
	ds_read_b128 v[222:225], v153 offset:51200
	ds_read_b128 v[226:229], v153 offset:52224
	buffer_load_dwordx4 v148, s[72:75], s8 offen lds
	s_mov_b32 m0, s86
	ds_read_b128 v[230:233], v153 offset:53248
	ds_read_b128 v[236:239], v153 offset:54272
	buffer_load_dwordx4 v146, s[72:75], s3 offen lds
	s_mov_b32 m0, s87
	ds_read_b128 v[240:243], v153 offset:55296
	ds_read_b128 v[244:247], v153 offset:56320
	buffer_load_dwordx4 v148, s[72:75], s3 offen lds
	s_waitcnt vmcnt(6)
	s_waitcnt lgkmcnt(0)
	s_barrier
	s_setprio 1
	s_waitcnt lgkmcnt(0)
	v_mfma_f32_16x16x32_bf16 v[30:33], v[12:15], v[38:41], v[138:141]
	v_mfma_f32_16x16x32_bf16 v[66:69], v[16:19], v[42:45], v[30:33]
	v_mfma_f32_16x16x32_bf16 v[4:7], v[12:15], v[240:243], v[4:7]
	v_mfma_f32_16x16x32_bf16 v[30:33], v[22:25], v[38:41], v[142:145]
	v_mfma_f32_16x16x32_bf16 v[62:65], v[26:29], v[42:45], v[30:33]
	v_mfma_f32_16x16x32_bf16 v[30:33], v[12:15], v[222:225], v[158:161]
	v_mfma_f32_16x16x32_bf16 v[50:53], v[16:19], v[226:229], v[30:33]
	v_mfma_f32_16x16x32_bf16 v[30:33], v[22:25], v[222:225], v[162:165]
	v_mfma_f32_16x16x32_bf16 v[46:49], v[26:29], v[226:229], v[30:33]
	v_mfma_f32_16x16x32_bf16 v[30:33], v[12:15], v[230:233], v[166:169]
	v_mfma_f32_16x16x32_bf16 v[34:37], v[16:19], v[236:239], v[30:33]
	v_mfma_f32_16x16x32_bf16 v[18:21], v[16:19], v[244:247], v[4:7]
	v_mfma_f32_16x16x32_bf16 v[30:33], v[22:25], v[230:233], v[170:173]
	v_mfma_f32_16x16x32_bf16 v[30:33], v[26:29], v[236:239], v[30:33]
	v_mfma_f32_16x16x32_bf16 v[4:7], v[22:25], v[240:243], v[8:11]
	v_mfma_f32_16x16x32_bf16 v[14:17], v[26:29], v[244:247], v[4:7]
	v_mfma_f32_16x16x32_bf16 v[4:7], v[206:209], v[38:41], v[174:177]
	v_mfma_f32_16x16x32_bf16 v[58:61], v[210:213], v[42:45], v[4:7]
	v_mfma_f32_16x16x32_bf16 v[4:7], v[214:217], v[38:41], v[178:181]
	v_mfma_f32_16x16x32_bf16 v[54:57], v[218:221], v[42:45], v[4:7]
	v_mfma_f32_16x16x32_bf16 v[4:7], v[206:209], v[222:225], v[182:185]
	v_mfma_f32_16x16x32_bf16 v[42:45], v[210:213], v[226:229], v[4:7]
	v_mfma_f32_16x16x32_bf16 v[4:7], v[214:217], v[222:225], v[186:189]
	v_mfma_f32_16x16x32_bf16 v[38:41], v[218:221], v[226:229], v[4:7]
	v_mfma_f32_16x16x32_bf16 v[4:7], v[206:209], v[230:233], v[190:193]
	v_mfma_f32_16x16x32_bf16 v[26:29], v[210:213], v[236:239], v[4:7]
	v_mfma_f32_16x16x32_bf16 v[4:7], v[214:217], v[230:233], v[194:197]
	v_mfma_f32_16x16x32_bf16 v[22:25], v[218:221], v[236:239], v[4:7]
	v_mfma_f32_16x16x32_bf16 v[4:7], v[206:209], v[240:243], v[198:201]
	v_mfma_f32_16x16x32_bf16 v[10:13], v[210:213], v[244:247], v[4:7]
	v_mfma_f32_16x16x32_bf16 v[4:7], v[214:217], v[240:243], v[202:205]
	v_mfma_f32_16x16x32_bf16 v[6:9], v[218:221], v[244:247], v[4:7]
	s_setprio 0
	s_barrier
	s_mov_b32 s9, 2
	s_branch .LBB0_123

.LBB0_124:
	ds_read_b128 v[138:141], v151
	ds_read_b128 v[142:145], v151 offset:1024
	ds_read_b128 v[158:161], v151 offset:2048
	ds_read_b128 v[162:165], v151 offset:3072
	ds_read_b128 v[166:169], v152
	ds_read_b128 v[170:173], v152 offset:1024
	ds_read_b128 v[174:177], v152 offset:2048
	ds_read_b128 v[178:181], v152 offset:3072
	s_add_i32 s47, s9, s10
	s_add_i32 s75, s47, 0x100
	s_add_i32 s13, s9, s11
	s_cmp_eq_u32 s9, s12
	s_cselect_b32 s13, s7, s13
	s_cselect_b32 s80, s6, s75
	s_add_i32 s75, s47, 0x80
	s_mov_b32 m0, s58
	ds_read_b128 v[182:185], v153
	ds_read_b128 v[186:189], v153 offset:1024
	buffer_load_dwordx4 v1, s[28:31], s75 offen lds
	s_mov_b32 m0, s59
	ds_read_b128 v[190:193], v153 offset:2048
	ds_read_b128 v[194:197], v153 offset:3072
	buffer_load_dwordx4 v147, s[28:31], s75 offen lds
	s_add_i32 s47, s47, 0x80080
	s_mov_b32 m0, s70
	ds_read_b128 v[198:201], v153 offset:4096
	ds_read_b128 v[202:205], v153 offset:5120
	buffer_load_dwordx4 v1, s[28:31], s47 offen lds
	s_mov_b32 m0, s71
	ds_read_b128 v[206:209], v153 offset:6144
	ds_read_b128 v[210:213], v153 offset:7168
	buffer_load_dwordx4 v147, s[28:31], s47 offen lds
	s_waitcnt vmcnt(8)
	s_waitcnt lgkmcnt(0)
	s_barrier
	s_setprio 1
	s_waitcnt lgkmcnt(0)
	v_mfma_f32_16x16x32_bf16 v[130:133], v[138:141], v[182:185], v[130:133]
	v_mfma_f32_16x16x32_bf16 v[130:133], v[142:145], v[186:189], v[130:133]
	v_mfma_f32_16x16x32_bf16 v[114:117], v[138:141], v[190:193], v[114:117]
	v_mfma_f32_16x16x32_bf16 v[114:117], v[142:145], v[194:197], v[114:117]
	v_mfma_f32_16x16x32_bf16 v[98:101], v[138:141], v[198:201], v[98:101]
	v_mfma_f32_16x16x32_bf16 v[98:101], v[142:145], v[202:205], v[98:101]
	v_mfma_f32_16x16x32_bf16 v[82:85], v[138:141], v[206:209], v[82:85]
	v_mfma_f32_16x16x32_bf16 v[82:85], v[142:145], v[210:213], v[82:85]
	v_mfma_f32_16x16x32_bf16 v[126:129], v[158:161], v[182:185], v[126:129]
	v_mfma_f32_16x16x32_bf16 v[126:129], v[162:165], v[186:189], v[126:129]
	v_mfma_f32_16x16x32_bf16 v[110:113], v[158:161], v[190:193], v[110:113]
	v_mfma_f32_16x16x32_bf16 v[110:113], v[162:165], v[194:197], v[110:113]
	v_mfma_f32_16x16x32_bf16 v[94:97], v[158:161], v[198:201], v[94:97]
	v_mfma_f32_16x16x32_bf16 v[94:97], v[162:165], v[202:205], v[94:97]
	v_mfma_f32_16x16x32_bf16 v[78:81], v[158:161], v[206:209], v[78:81]
	v_mfma_f32_16x16x32_bf16 v[78:81], v[162:165], v[210:213], v[78:81]
	v_mfma_f32_16x16x32_bf16 v[122:125], v[166:169], v[182:185], v[122:125]
	v_mfma_f32_16x16x32_bf16 v[122:125], v[170:173], v[186:189], v[122:125]
	v_mfma_f32_16x16x32_bf16 v[106:109], v[166:169], v[190:193], v[106:109]
	v_mfma_f32_16x16x32_bf16 v[106:109], v[170:173], v[194:197], v[106:109]
	v_mfma_f32_16x16x32_bf16 v[90:93], v[166:169], v[198:201], v[90:93]
	v_mfma_f32_16x16x32_bf16 v[90:93], v[170:173], v[202:205], v[90:93]
	v_mfma_f32_16x16x32_bf16 v[74:77], v[166:169], v[206:209], v[74:77]
	v_mfma_f32_16x16x32_bf16 v[74:77], v[170:173], v[210:213], v[74:77]
	v_mfma_f32_16x16x32_bf16 v[118:121], v[174:177], v[182:185], v[118:121]
	v_mfma_f32_16x16x32_bf16 v[118:121], v[178:181], v[186:189], v[118:121]
	v_mfma_f32_16x16x32_bf16 v[102:105], v[174:177], v[190:193], v[102:105]
	v_mfma_f32_16x16x32_bf16 v[102:105], v[178:181], v[194:197], v[102:105]
	v_mfma_f32_16x16x32_bf16 v[86:89], v[174:177], v[198:201], v[86:89]
	v_mfma_f32_16x16x32_bf16 v[86:89], v[178:181], v[202:205], v[86:89]
	v_mfma_f32_16x16x32_bf16 v[70:73], v[174:177], v[206:209], v[70:73]
	v_mfma_f32_16x16x32_bf16 v[70:73], v[178:181], v[210:213], v[70:73]
	s_setprio 0
	s_barrier
	s_mov_b32 m0, s91
	s_mov_b32 s75, s31
	ds_read_b128 v[182:185], v153 offset:16384
	ds_read_b128 v[186:189], v153 offset:17408
	buffer_load_dwordx4 v146, s[72:75], s13 offen lds
	s_mov_b32 m0, s93
	ds_read_b128 v[190:193], v153 offset:18432
	ds_read_b128 v[194:197], v153 offset:19456
	buffer_load_dwordx4 v148, s[72:75], s13 offen lds
	s_add_i32 s47, s13, 0x80000
	s_mov_b32 m0, s95
	ds_read_b128 v[198:201], v153 offset:20480
	ds_read_b128 v[202:205], v153 offset:21504
	buffer_load_dwordx4 v146, s[72:75], s47 offen lds
	s_mov_b32 m0, s35
	ds_read_b128 v[206:209], v153 offset:22528
	ds_read_b128 v[210:213], v153 offset:23552
	buffer_load_dwordx4 v148, s[72:75], s47 offen lds
	s_waitcnt vmcnt(6)
	s_waitcnt lgkmcnt(0)
	s_barrier
	s_setprio 1
	s_waitcnt lgkmcnt(0)
	v_mfma_f32_16x16x32_bf16 v[66:69], v[138:141], v[182:185], v[66:69]
	v_mfma_f32_16x16x32_bf16 v[66:69], v[142:145], v[186:189], v[66:69]
	v_mfma_f32_16x16x32_bf16 v[50:53], v[138:141], v[190:193], v[50:53]
	v_mfma_f32_16x16x32_bf16 v[50:53], v[142:145], v[194:197], v[50:53]
	v_mfma_f32_16x16x32_bf16 v[34:37], v[138:141], v[198:201], v[34:37]
	v_mfma_f32_16x16x32_bf16 v[34:37], v[142:145], v[202:205], v[34:37]
	v_mfma_f32_16x16x32_bf16 v[18:21], v[138:141], v[206:209], v[18:21]
	v_mfma_f32_16x16x32_bf16 v[18:21], v[142:145], v[210:213], v[18:21]
	v_mfma_f32_16x16x32_bf16 v[62:65], v[158:161], v[182:185], v[62:65]
	v_mfma_f32_16x16x32_bf16 v[62:65], v[162:165], v[186:189], v[62:65]
	v_mfma_f32_16x16x32_bf16 v[46:49], v[158:161], v[190:193], v[46:49]
	v_mfma_f32_16x16x32_bf16 v[46:49], v[162:165], v[194:197], v[46:49]
	v_mfma_f32_16x16x32_bf16 v[30:33], v[158:161], v[198:201], v[30:33]
	v_mfma_f32_16x16x32_bf16 v[30:33], v[162:165], v[202:205], v[30:33]
	v_mfma_f32_16x16x32_bf16 v[14:17], v[158:161], v[206:209], v[14:17]
	v_mfma_f32_16x16x32_bf16 v[14:17], v[162:165], v[210:213], v[14:17]
	v_mfma_f32_16x16x32_bf16 v[58:61], v[166:169], v[182:185], v[58:61]
	v_mfma_f32_16x16x32_bf16 v[58:61], v[170:173], v[186:189], v[58:61]
	v_mfma_f32_16x16x32_bf16 v[42:45], v[166:169], v[190:193], v[42:45]
	v_mfma_f32_16x16x32_bf16 v[42:45], v[170:173], v[194:197], v[42:45]
	v_mfma_f32_16x16x32_bf16 v[26:29], v[166:169], v[198:201], v[26:29]
	v_mfma_f32_16x16x32_bf16 v[26:29], v[170:173], v[202:205], v[26:29]
	v_mfma_f32_16x16x32_bf16 v[10:13], v[166:169], v[206:209], v[10:13]
	v_mfma_f32_16x16x32_bf16 v[10:13], v[170:173], v[210:213], v[10:13]
	v_mfma_f32_16x16x32_bf16 v[54:57], v[174:177], v[182:185], v[54:57]
	v_mfma_f32_16x16x32_bf16 v[54:57], v[178:181], v[186:189], v[54:57]
	v_mfma_f32_16x16x32_bf16 v[38:41], v[174:177], v[190:193], v[38:41]
	v_mfma_f32_16x16x32_bf16 v[38:41], v[178:181], v[194:197], v[38:41]
	v_mfma_f32_16x16x32_bf16 v[22:25], v[174:177], v[198:201], v[22:25]
	v_mfma_f32_16x16x32_bf16 v[22:25], v[178:181], v[202:205], v[22:25]
	v_mfma_f32_16x16x32_bf16 v[4:7], v[174:177], v[206:209], v[6:9]
	v_mfma_f32_16x16x32_bf16 v[4:7], v[178:181], v[210:213], v[4:7]
	s_setprio 0
	s_barrier
	ds_read_b128 v[138:141], v154
	ds_read_b128 v[142:145], v154 offset:1024
	ds_read_b128 v[158:161], v154 offset:2048
	ds_read_b128 v[162:165], v154 offset:3072
	ds_read_b128 v[166:169], v155
	ds_read_b128 v[170:173], v155 offset:1024
	ds_read_b128 v[174:177], v155 offset:2048
	ds_read_b128 v[178:181], v155 offset:3072
	s_mov_b32 m0, s77
	ds_read_b128 v[182:185], v153 offset:32768
	ds_read_b128 v[186:189], v153 offset:33792
	buffer_load_dwordx4 v1, s[28:31], s80 offen lds
	s_mov_b32 m0, s84
	ds_read_b128 v[190:193], v153 offset:34816
	ds_read_b128 v[194:197], v153 offset:35840
	buffer_load_dwordx4 v147, s[28:31], s80 offen lds
	s_add_i32 s80, s80, 0x80000
	s_mov_b32 m0, s85
	ds_read_b128 v[198:201], v153 offset:36864
	ds_read_b128 v[202:205], v153 offset:37888
	buffer_load_dwordx4 v1, s[28:31], s80 offen lds
	s_mov_b32 m0, s48
	ds_read_b128 v[206:209], v153 offset:38912
	ds_read_b128 v[210:213], v153 offset:39936
	buffer_load_dwordx4 v147, s[28:31], s80 offen lds
	s_waitcnt vmcnt(8)
	s_waitcnt lgkmcnt(0)
	s_barrier
	s_setprio 1
	s_waitcnt lgkmcnt(0)
	v_mfma_f32_16x16x32_bf16 v[130:133], v[138:141], v[182:185], v[130:133]
	v_mfma_f32_16x16x32_bf16 v[130:133], v[142:145], v[186:189], v[130:133]
	v_mfma_f32_16x16x32_bf16 v[114:117], v[138:141], v[190:193], v[114:117]
	v_mfma_f32_16x16x32_bf16 v[114:117], v[142:145], v[194:197], v[114:117]
	v_mfma_f32_16x16x32_bf16 v[98:101], v[138:141], v[198:201], v[98:101]
	v_mfma_f32_16x16x32_bf16 v[98:101], v[142:145], v[202:205], v[98:101]
	v_mfma_f32_16x16x32_bf16 v[82:85], v[138:141], v[206:209], v[82:85]
	v_mfma_f32_16x16x32_bf16 v[82:85], v[142:145], v[210:213], v[82:85]
	v_mfma_f32_16x16x32_bf16 v[126:129], v[158:161], v[182:185], v[126:129]
	v_mfma_f32_16x16x32_bf16 v[126:129], v[162:165], v[186:189], v[126:129]
	v_mfma_f32_16x16x32_bf16 v[110:113], v[158:161], v[190:193], v[110:113]
	v_mfma_f32_16x16x32_bf16 v[110:113], v[162:165], v[194:197], v[110:113]
	v_mfma_f32_16x16x32_bf16 v[94:97], v[158:161], v[198:201], v[94:97]
	v_mfma_f32_16x16x32_bf16 v[94:97], v[162:165], v[202:205], v[94:97]
	v_mfma_f32_16x16x32_bf16 v[78:81], v[158:161], v[206:209], v[78:81]
	v_mfma_f32_16x16x32_bf16 v[78:81], v[162:165], v[210:213], v[78:81]
	v_mfma_f32_16x16x32_bf16 v[122:125], v[166:169], v[182:185], v[122:125]
	v_mfma_f32_16x16x32_bf16 v[122:125], v[170:173], v[186:189], v[122:125]
	v_mfma_f32_16x16x32_bf16 v[106:109], v[166:169], v[190:193], v[106:109]
	v_mfma_f32_16x16x32_bf16 v[106:109], v[170:173], v[194:197], v[106:109]
	v_mfma_f32_16x16x32_bf16 v[90:93], v[166:169], v[198:201], v[90:93]
	v_mfma_f32_16x16x32_bf16 v[90:93], v[170:173], v[202:205], v[90:93]
	v_mfma_f32_16x16x32_bf16 v[74:77], v[166:169], v[206:209], v[74:77]
	v_mfma_f32_16x16x32_bf16 v[74:77], v[170:173], v[210:213], v[74:77]
	v_mfma_f32_16x16x32_bf16 v[118:121], v[174:177], v[182:185], v[118:121]
	v_mfma_f32_16x16x32_bf16 v[118:121], v[178:181], v[186:189], v[118:121]
	v_mfma_f32_16x16x32_bf16 v[102:105], v[174:177], v[190:193], v[102:105]
	v_mfma_f32_16x16x32_bf16 v[102:105], v[178:181], v[194:197], v[102:105]
	v_mfma_f32_16x16x32_bf16 v[86:89], v[174:177], v[198:201], v[86:89]
	v_mfma_f32_16x16x32_bf16 v[86:89], v[178:181], v[202:205], v[86:89]
	v_mfma_f32_16x16x32_bf16 v[70:73], v[174:177], v[206:209], v[70:73]
	v_mfma_f32_16x16x32_bf16 v[70:73], v[178:181], v[210:213], v[70:73]
	s_setprio 0
	s_barrier
	s_mov_b32 m0, s78
	s_add_i32 s47, s13, 0x80
	ds_read_b128 v[182:185], v153 offset:49152
	ds_read_b128 v[186:189], v153 offset:50176
	buffer_load_dwordx4 v146, s[72:75], s47 offen lds
	s_mov_b32 m0, s79
	ds_read_b128 v[190:193], v153 offset:51200
	ds_read_b128 v[194:197], v153 offset:52224
	buffer_load_dwordx4 v148, s[72:75], s47 offen lds
	s_add_i32 s13, s13, 0x80080
	s_mov_b32 m0, s86
	ds_read_b128 v[198:201], v153 offset:53248
	ds_read_b128 v[202:205], v153 offset:54272
	buffer_load_dwordx4 v146, s[72:75], s13 offen lds
	s_mov_b32 m0, s87
	ds_read_b128 v[206:209], v153 offset:55296
	ds_read_b128 v[210:213], v153 offset:56320
	buffer_load_dwordx4 v148, s[72:75], s13 offen lds
	s_waitcnt vmcnt(6)
	s_waitcnt lgkmcnt(0)
	s_barrier
	s_setprio 1
	s_waitcnt lgkmcnt(0)
	v_mfma_f32_16x16x32_bf16 v[66:69], v[138:141], v[182:185], v[66:69]
	v_mfma_f32_16x16x32_bf16 v[66:69], v[142:145], v[186:189], v[66:69]
	v_mfma_f32_16x16x32_bf16 v[50:53], v[138:141], v[190:193], v[50:53]
	v_mfma_f32_16x16x32_bf16 v[50:53], v[142:145], v[194:197], v[50:53]
	v_mfma_f32_16x16x32_bf16 v[34:37], v[138:141], v[198:201], v[34:37]
	v_mfma_f32_16x16x32_bf16 v[34:37], v[142:145], v[202:205], v[34:37]
	v_mfma_f32_16x16x32_bf16 v[18:21], v[138:141], v[206:209], v[18:21]
	v_mfma_f32_16x16x32_bf16 v[18:21], v[142:145], v[210:213], v[18:21]
	v_mfma_f32_16x16x32_bf16 v[62:65], v[158:161], v[182:185], v[62:65]
	v_mfma_f32_16x16x32_bf16 v[62:65], v[162:165], v[186:189], v[62:65]
	v_mfma_f32_16x16x32_bf16 v[46:49], v[158:161], v[190:193], v[46:49]
	v_mfma_f32_16x16x32_bf16 v[46:49], v[162:165], v[194:197], v[46:49]
	v_mfma_f32_16x16x32_bf16 v[30:33], v[158:161], v[198:201], v[30:33]
	v_mfma_f32_16x16x32_bf16 v[30:33], v[162:165], v[202:205], v[30:33]
	v_mfma_f32_16x16x32_bf16 v[14:17], v[158:161], v[206:209], v[14:17]
	v_mfma_f32_16x16x32_bf16 v[14:17], v[162:165], v[210:213], v[14:17]
	v_mfma_f32_16x16x32_bf16 v[58:61], v[166:169], v[182:185], v[58:61]
	v_mfma_f32_16x16x32_bf16 v[58:61], v[170:173], v[186:189], v[58:61]
	v_mfma_f32_16x16x32_bf16 v[42:45], v[166:169], v[190:193], v[42:45]
	v_mfma_f32_16x16x32_bf16 v[42:45], v[170:173], v[194:197], v[42:45]
	v_mfma_f32_16x16x32_bf16 v[26:29], v[166:169], v[198:201], v[26:29]
	v_mfma_f32_16x16x32_bf16 v[26:29], v[170:173], v[202:205], v[26:29]
	v_mfma_f32_16x16x32_bf16 v[8:11], v[166:169], v[206:209], v[10:13]
	v_mfma_f32_16x16x32_bf16 v[10:13], v[170:173], v[210:213], v[8:11]
	v_mfma_f32_16x16x32_bf16 v[54:57], v[174:177], v[182:185], v[54:57]
	v_mfma_f32_16x16x32_bf16 v[54:57], v[178:181], v[186:189], v[54:57]
	v_mfma_f32_16x16x32_bf16 v[38:41], v[174:177], v[190:193], v[38:41]
	v_mfma_f32_16x16x32_bf16 v[38:41], v[178:181], v[194:197], v[38:41]
	v_mfma_f32_16x16x32_bf16 v[22:25], v[174:177], v[198:201], v[22:25]
	v_mfma_f32_16x16x32_bf16 v[22:25], v[178:181], v[202:205], v[22:25]
	v_mfma_f32_16x16x32_bf16 v[4:7], v[174:177], v[206:209], v[4:7]
	v_mfma_f32_16x16x32_bf16 v[6:9], v[178:181], v[210:213], v[4:7]
	s_setprio 0
	s_barrier
	s_add_i32 s8, s8, 2
	s_addk_i32 s10, 0x100
	s_addk_i32 s11, 0x100
	s_addk_i32 s12, 0xff00
	s_cmp_gt_u32 s8, 29
	s_cbranch_scc0 .LBB0_124
	v_readlane_b32 s6, v254, 26
	v_readlane_b32 s7, v254, 27
	s_and_b64 vcc, exec, s[6:7]
	s_cbranch_vccz .LBB0_127
	s_barrier

.LBB0_528:
	v_add_u32_e32 v3, 0x10000, v171
	ds_read_b128 v[134:137], v3
	ds_read_b128 v[138:141], v3 offset:1024
	ds_read_b128 v[142:145], v3 offset:2048
	ds_read_b128 v[146:149], v3 offset:3072
	v_add_u32_e32 v3, 0x14000, v171
	ds_read_b128 v[150:153], v3
	ds_read_b128 v[154:157], v3 offset:1024
	ds_read_b128 v[174:177], v3 offset:2048
	ds_read_b128 v[178:181], v3 offset:3072
	s_add_i32 s71, s63, s94
	s_add_i32 s97, s71, 0x100
	s_add_i32 s96, s63, s95
	s_cmp_eq_u32 s63, s93
	s_cselect_b32 s96, s90, s96
	s_cselect_b32 s97, s89, s97
	s_add_i32 vcc_lo, s71, 0x80
	s_mov_b32 m0, s79
	ds_read_b128 v[182:185], v172
	ds_read_b128 v[186:189], v172 offset:1024
	buffer_load_dwordx4 v1, s[48:51], vcc_lo offen lds
	s_mov_b32 m0, s80
	ds_read_b128 v[190:193], v172 offset:2048
	ds_read_b128 v[194:197], v172 offset:3072
	buffer_load_dwordx4 v167, s[48:51], vcc_lo offen lds
	s_add_i32 s71, s71, 0xc0080
	s_mov_b32 m0, s81
	ds_read_b128 v[198:201], v172 offset:4096
	ds_read_b128 v[202:205], v172 offset:5120
	buffer_load_dwordx4 v1, s[48:51], s71 offen lds
	s_mov_b32 m0, s82
	ds_read_b128 v[206:209], v172 offset:6144
	ds_read_b128 v[210:213], v172 offset:7168
	buffer_load_dwordx4 v167, s[48:51], s71 offen lds
	s_waitcnt vmcnt(8)
	s_waitcnt lgkmcnt(0)
	s_barrier
	s_setprio 1
	s_waitcnt lgkmcnt(0)
	v_mfma_f32_16x16x32_bf16 v[130:133], v[134:137], v[182:185], v[130:133]
	v_mfma_f32_16x16x32_bf16 v[130:133], v[138:141], v[186:189], v[130:133]
	v_mfma_f32_16x16x32_bf16 v[114:117], v[134:137], v[190:193], v[114:117]
	v_mfma_f32_16x16x32_bf16 v[114:117], v[138:141], v[194:197], v[114:117]
	v_mfma_f32_16x16x32_bf16 v[98:101], v[134:137], v[198:201], v[98:101]
	v_mfma_f32_16x16x32_bf16 v[98:101], v[138:141], v[202:205], v[98:101]
	v_mfma_f32_16x16x32_bf16 v[82:85], v[134:137], v[206:209], v[82:85]
	v_mfma_f32_16x16x32_bf16 v[82:85], v[138:141], v[210:213], v[82:85]
	v_mfma_f32_16x16x32_bf16 v[126:129], v[142:145], v[182:185], v[126:129]
	v_mfma_f32_16x16x32_bf16 v[126:129], v[146:149], v[186:189], v[126:129]
	v_mfma_f32_16x16x32_bf16 v[110:113], v[142:145], v[190:193], v[110:113]
	v_mfma_f32_16x16x32_bf16 v[110:113], v[146:149], v[194:197], v[110:113]
	v_mfma_f32_16x16x32_bf16 v[94:97], v[142:145], v[198:201], v[94:97]
	v_mfma_f32_16x16x32_bf16 v[94:97], v[146:149], v[202:205], v[94:97]
	v_mfma_f32_16x16x32_bf16 v[78:81], v[142:145], v[206:209], v[78:81]
	v_mfma_f32_16x16x32_bf16 v[78:81], v[146:149], v[210:213], v[78:81]
	v_mfma_f32_16x16x32_bf16 v[122:125], v[150:153], v[182:185], v[122:125]
	v_mfma_f32_16x16x32_bf16 v[122:125], v[154:157], v[186:189], v[122:125]
	v_mfma_f32_16x16x32_bf16 v[106:109], v[150:153], v[190:193], v[106:109]
	v_mfma_f32_16x16x32_bf16 v[106:109], v[154:157], v[194:197], v[106:109]
	v_mfma_f32_16x16x32_bf16 v[90:93], v[150:153], v[198:201], v[90:93]
	v_mfma_f32_16x16x32_bf16 v[90:93], v[154:157], v[202:205], v[90:93]
	v_mfma_f32_16x16x32_bf16 v[74:77], v[150:153], v[206:209], v[74:77]
	v_mfma_f32_16x16x32_bf16 v[74:77], v[154:157], v[210:213], v[74:77]
	v_mfma_f32_16x16x32_bf16 v[118:121], v[174:177], v[182:185], v[118:121]
	v_mfma_f32_16x16x32_bf16 v[118:121], v[178:181], v[186:189], v[118:121]
	v_mfma_f32_16x16x32_bf16 v[102:105], v[174:177], v[190:193], v[102:105]
	v_mfma_f32_16x16x32_bf16 v[102:105], v[178:181], v[194:197], v[102:105]
	v_mfma_f32_16x16x32_bf16 v[86:89], v[174:177], v[198:201], v[86:89]
	v_mfma_f32_16x16x32_bf16 v[86:89], v[178:181], v[202:205], v[86:89]
	v_mfma_f32_16x16x32_bf16 v[70:73], v[174:177], v[206:209], v[70:73]
	v_mfma_f32_16x16x32_bf16 v[70:73], v[178:181], v[210:213], v[70:73]
	s_setprio 0
	s_barrier
	s_mov_b32 m0, s35
	s_mov_b32 s71, s51
	ds_read_b128 v[182:185], v172 offset:16384
	ds_read_b128 v[186:189], v172 offset:17408
	buffer_load_dwordx4 v166, s[68:71], s96 offen lds
	s_mov_b32 m0, s45
	ds_read_b128 v[190:193], v172 offset:18432
	ds_read_b128 v[194:197], v172 offset:19456
	buffer_load_dwordx4 v168, s[68:71], s96 offen lds
	s_add_i32 vcc_lo, s96, 0xc0000
	s_mov_b32 m0, s64
	ds_read_b128 v[198:201], v172 offset:20480
	ds_read_b128 v[202:205], v172 offset:21504
	buffer_load_dwordx4 v166, s[68:71], vcc_lo offen lds
	s_mov_b32 m0, s65
	ds_read_b128 v[206:209], v172 offset:22528
	ds_read_b128 v[210:213], v172 offset:23552
	buffer_load_dwordx4 v168, s[68:71], vcc_lo offen lds
	s_waitcnt vmcnt(6)
	s_waitcnt lgkmcnt(0)
	s_barrier
	s_setprio 1
	s_waitcnt lgkmcnt(0)
	v_mfma_f32_16x16x32_bf16 v[66:69], v[134:137], v[182:185], v[66:69]
	v_mfma_f32_16x16x32_bf16 v[66:69], v[138:141], v[186:189], v[66:69]
	v_mfma_f32_16x16x32_bf16 v[50:53], v[134:137], v[190:193], v[50:53]
	v_mfma_f32_16x16x32_bf16 v[50:53], v[138:141], v[194:197], v[50:53]
	v_mfma_f32_16x16x32_bf16 v[34:37], v[134:137], v[198:201], v[34:37]
	v_mfma_f32_16x16x32_bf16 v[34:37], v[138:141], v[202:205], v[34:37]
	v_mfma_f32_16x16x32_bf16 v[18:21], v[134:137], v[206:209], v[18:21]
	v_mfma_f32_16x16x32_bf16 v[18:21], v[138:141], v[210:213], v[18:21]
	v_mfma_f32_16x16x32_bf16 v[62:65], v[142:145], v[182:185], v[62:65]
	v_mfma_f32_16x16x32_bf16 v[62:65], v[146:149], v[186:189], v[62:65]
	v_mfma_f32_16x16x32_bf16 v[46:49], v[142:145], v[190:193], v[46:49]
	v_mfma_f32_16x16x32_bf16 v[46:49], v[146:149], v[194:197], v[46:49]
	v_mfma_f32_16x16x32_bf16 v[30:33], v[142:145], v[198:201], v[30:33]
	v_mfma_f32_16x16x32_bf16 v[30:33], v[146:149], v[202:205], v[30:33]
	v_mfma_f32_16x16x32_bf16 v[14:17], v[142:145], v[206:209], v[14:17]
	v_mfma_f32_16x16x32_bf16 v[14:17], v[146:149], v[210:213], v[14:17]
	v_mfma_f32_16x16x32_bf16 v[58:61], v[150:153], v[182:185], v[58:61]
	v_mfma_f32_16x16x32_bf16 v[58:61], v[154:157], v[186:189], v[58:61]
	v_mfma_f32_16x16x32_bf16 v[42:45], v[150:153], v[190:193], v[42:45]
	v_mfma_f32_16x16x32_bf16 v[42:45], v[154:157], v[194:197], v[42:45]
	v_mfma_f32_16x16x32_bf16 v[26:29], v[150:153], v[198:201], v[26:29]
	v_mfma_f32_16x16x32_bf16 v[26:29], v[154:157], v[202:205], v[26:29]
	v_mfma_f32_16x16x32_bf16 v[10:13], v[150:153], v[206:209], v[10:13]
	v_mfma_f32_16x16x32_bf16 v[10:13], v[154:157], v[210:213], v[10:13]
	v_mfma_f32_16x16x32_bf16 v[54:57], v[174:177], v[182:185], v[54:57]
	v_mfma_f32_16x16x32_bf16 v[54:57], v[178:181], v[186:189], v[54:57]
	v_mfma_f32_16x16x32_bf16 v[38:41], v[174:177], v[190:193], v[38:41]
	v_mfma_f32_16x16x32_bf16 v[38:41], v[178:181], v[194:197], v[38:41]
	v_mfma_f32_16x16x32_bf16 v[22:25], v[174:177], v[198:201], v[22:25]
	v_mfma_f32_16x16x32_bf16 v[22:25], v[178:181], v[202:205], v[22:25]
	v_mfma_f32_16x16x32_bf16 v[4:7], v[174:177], v[206:209], v[6:9]
	v_mfma_f32_16x16x32_bf16 v[4:7], v[178:181], v[210:213], v[4:7]
	s_setprio 0
	s_barrier
	v_add_u32_e32 v3, 0x18000, v171
	ds_read_b128 v[134:137], v3
	ds_read_b128 v[138:141], v3 offset:1024
	ds_read_b128 v[142:145], v3 offset:2048
	ds_read_b128 v[146:149], v3 offset:3072
	v_add_u32_e32 v3, 0x1c000, v171
	ds_read_b128 v[150:153], v3
	ds_read_b128 v[154:157], v3 offset:1024
	ds_read_b128 v[174:177], v3 offset:2048
	ds_read_b128 v[178:181], v3 offset:3072
	s_mov_b32 m0, s29
	ds_read_b128 v[182:185], v172 offset:32768
	ds_read_b128 v[186:189], v172 offset:33792
	buffer_load_dwordx4 v1, s[48:51], s97 offen lds
	s_mov_b32 m0, s66
	ds_read_b128 v[190:193], v172 offset:34816
	ds_read_b128 v[194:197], v172 offset:35840
	buffer_load_dwordx4 v167, s[48:51], s97 offen lds
	s_add_i32 s97, s97, 0xc0000
	s_mov_b32 m0, s67
	ds_read_b128 v[198:201], v172 offset:36864
	ds_read_b128 v[202:205], v172 offset:37888
	buffer_load_dwordx4 v1, s[48:51], s97 offen lds
	s_mov_b32 m0, s72
	ds_read_b128 v[206:209], v172 offset:38912
	ds_read_b128 v[210:213], v172 offset:39936
	buffer_load_dwordx4 v167, s[48:51], s97 offen lds
	s_waitcnt vmcnt(8)
	s_waitcnt lgkmcnt(0)
	s_barrier
	s_setprio 1
	s_waitcnt lgkmcnt(0)
	v_mfma_f32_16x16x32_bf16 v[130:133], v[134:137], v[182:185], v[130:133]
	v_mfma_f32_16x16x32_bf16 v[130:133], v[138:141], v[186:189], v[130:133]
	v_mfma_f32_16x16x32_bf16 v[114:117], v[134:137], v[190:193], v[114:117]
	v_mfma_f32_16x16x32_bf16 v[114:117], v[138:141], v[194:197], v[114:117]
	v_mfma_f32_16x16x32_bf16 v[98:101], v[134:137], v[198:201], v[98:101]
	v_mfma_f32_16x16x32_bf16 v[98:101], v[138:141], v[202:205], v[98:101]
	v_mfma_f32_16x16x32_bf16 v[82:85], v[134:137], v[206:209], v[82:85]
	v_mfma_f32_16x16x32_bf16 v[82:85], v[138:141], v[210:213], v[82:85]
	v_mfma_f32_16x16x32_bf16 v[126:129], v[142:145], v[182:185], v[126:129]
	v_mfma_f32_16x16x32_bf16 v[126:129], v[146:149], v[186:189], v[126:129]
	v_mfma_f32_16x16x32_bf16 v[110:113], v[142:145], v[190:193], v[110:113]
	v_mfma_f32_16x16x32_bf16 v[110:113], v[146:149], v[194:197], v[110:113]
	v_mfma_f32_16x16x32_bf16 v[94:97], v[142:145], v[198:201], v[94:97]
	v_mfma_f32_16x16x32_bf16 v[94:97], v[146:149], v[202:205], v[94:97]
	v_mfma_f32_16x16x32_bf16 v[78:81], v[142:145], v[206:209], v[78:81]
	v_mfma_f32_16x16x32_bf16 v[78:81], v[146:149], v[210:213], v[78:81]
	v_mfma_f32_16x16x32_bf16 v[122:125], v[150:153], v[182:185], v[122:125]
	v_mfma_f32_16x16x32_bf16 v[122:125], v[154:157], v[186:189], v[122:125]
	v_mfma_f32_16x16x32_bf16 v[106:109], v[150:153], v[190:193], v[106:109]
	v_mfma_f32_16x16x32_bf16 v[106:109], v[154:157], v[194:197], v[106:109]
	v_mfma_f32_16x16x32_bf16 v[90:93], v[150:153], v[198:201], v[90:93]
	v_mfma_f32_16x16x32_bf16 v[90:93], v[154:157], v[202:205], v[90:93]
	v_mfma_f32_16x16x32_bf16 v[74:77], v[150:153], v[206:209], v[74:77]
	v_mfma_f32_16x16x32_bf16 v[74:77], v[154:157], v[210:213], v[74:77]
	v_mfma_f32_16x16x32_bf16 v[118:121], v[174:177], v[182:185], v[118:121]
	v_mfma_f32_16x16x32_bf16 v[118:121], v[178:181], v[186:189], v[118:121]
	v_mfma_f32_16x16x32_bf16 v[102:105], v[174:177], v[190:193], v[102:105]
	v_mfma_f32_16x16x32_bf16 v[102:105], v[178:181], v[194:197], v[102:105]
	v_mfma_f32_16x16x32_bf16 v[86:89], v[174:177], v[198:201], v[86:89]
	v_mfma_f32_16x16x32_bf16 v[86:89], v[178:181], v[202:205], v[86:89]
	v_mfma_f32_16x16x32_bf16 v[70:73], v[174:177], v[206:209], v[70:73]
	v_mfma_f32_16x16x32_bf16 v[70:73], v[178:181], v[210:213], v[70:73]
	s_setprio 0
	s_barrier
	s_mov_b32 m0, s74
	s_add_i32 s97, s96, 0x80
	ds_read_b128 v[182:185], v172 offset:49152
	ds_read_b128 v[186:189], v172 offset:50176
	buffer_load_dwordx4 v166, s[68:71], s97 offen lds
	s_mov_b32 m0, s75
	ds_read_b128 v[190:193], v172 offset:51200
	ds_read_b128 v[194:197], v172 offset:52224
	buffer_load_dwordx4 v168, s[68:71], s97 offen lds
	s_add_i32 s96, s96, 0xc0080
	s_mov_b32 m0, s77
	ds_read_b128 v[198:201], v172 offset:53248
	ds_read_b128 v[202:205], v172 offset:54272
	buffer_load_dwordx4 v166, s[68:71], s96 offen lds
	s_mov_b32 m0, s78
	ds_read_b128 v[206:209], v172 offset:55296
	ds_read_b128 v[210:213], v172 offset:56320
	buffer_load_dwordx4 v168, s[68:71], s96 offen lds
	s_waitcnt vmcnt(6)
	s_waitcnt lgkmcnt(0)
	s_barrier
	s_setprio 1
	s_waitcnt lgkmcnt(0)
	v_mfma_f32_16x16x32_bf16 v[66:69], v[134:137], v[182:185], v[66:69]
	v_mfma_f32_16x16x32_bf16 v[66:69], v[138:141], v[186:189], v[66:69]
	v_mfma_f32_16x16x32_bf16 v[50:53], v[134:137], v[190:193], v[50:53]
	v_mfma_f32_16x16x32_bf16 v[50:53], v[138:141], v[194:197], v[50:53]
	v_mfma_f32_16x16x32_bf16 v[34:37], v[134:137], v[198:201], v[34:37]
	v_mfma_f32_16x16x32_bf16 v[34:37], v[138:141], v[202:205], v[34:37]
	v_mfma_f32_16x16x32_bf16 v[18:21], v[134:137], v[206:209], v[18:21]
	v_mfma_f32_16x16x32_bf16 v[18:21], v[138:141], v[210:213], v[18:21]
	v_mfma_f32_16x16x32_bf16 v[62:65], v[142:145], v[182:185], v[62:65]
	v_mfma_f32_16x16x32_bf16 v[62:65], v[146:149], v[186:189], v[62:65]
	v_mfma_f32_16x16x32_bf16 v[46:49], v[142:145], v[190:193], v[46:49]
	v_mfma_f32_16x16x32_bf16 v[46:49], v[146:149], v[194:197], v[46:49]
	v_mfma_f32_16x16x32_bf16 v[30:33], v[142:145], v[198:201], v[30:33]
	v_mfma_f32_16x16x32_bf16 v[30:33], v[146:149], v[202:205], v[30:33]
	v_mfma_f32_16x16x32_bf16 v[14:17], v[142:145], v[206:209], v[14:17]
	v_mfma_f32_16x16x32_bf16 v[14:17], v[146:149], v[210:213], v[14:17]
	v_mfma_f32_16x16x32_bf16 v[58:61], v[150:153], v[182:185], v[58:61]
	v_mfma_f32_16x16x32_bf16 v[58:61], v[154:157], v[186:189], v[58:61]
	v_mfma_f32_16x16x32_bf16 v[42:45], v[150:153], v[190:193], v[42:45]
	v_mfma_f32_16x16x32_bf16 v[42:45], v[154:157], v[194:197], v[42:45]
	v_mfma_f32_16x16x32_bf16 v[26:29], v[150:153], v[198:201], v[26:29]
	v_mfma_f32_16x16x32_bf16 v[26:29], v[154:157], v[202:205], v[26:29]
	v_mfma_f32_16x16x32_bf16 v[8:11], v[150:153], v[206:209], v[10:13]
	v_mfma_f32_16x16x32_bf16 v[10:13], v[154:157], v[210:213], v[8:11]
	v_mfma_f32_16x16x32_bf16 v[54:57], v[174:177], v[182:185], v[54:57]
	v_mfma_f32_16x16x32_bf16 v[54:57], v[178:181], v[186:189], v[54:57]
	v_mfma_f32_16x16x32_bf16 v[38:41], v[174:177], v[190:193], v[38:41]
	v_mfma_f32_16x16x32_bf16 v[38:41], v[178:181], v[194:197], v[38:41]
	v_mfma_f32_16x16x32_bf16 v[22:25], v[174:177], v[198:201], v[22:25]
	v_mfma_f32_16x16x32_bf16 v[22:25], v[178:181], v[202:205], v[22:25]
	v_mfma_f32_16x16x32_bf16 v[4:7], v[174:177], v[206:209], v[4:7]
	v_mfma_f32_16x16x32_bf16 v[6:9], v[178:181], v[210:213], v[4:7]
	s_setprio 0
	s_barrier
	s_add_i32 s92, s92, 2
	s_addk_i32 s95, 0x100
	s_addk_i32 s94, 0x100
	s_addk_i32 s93, 0xff00
	s_cmp_ge_u32 s92, s62
	s_cbranch_scc0 .LBB0_528
	s_branch .LBB0_523

.LBB0_605:
	v_add_u32_e32 v141, 0x10000, v139
	ds_read_b128 v[142:145], v141
	ds_read_b128 v[146:149], v141 offset:1024
	ds_read_b128 v[154:157], v141 offset:2048
	ds_read_b128 v[158:161], v141 offset:3072
	v_add_u32_e32 v141, 0x14000, v139
	ds_read_b128 v[162:165], v141
	ds_read_b128 v[166:169], v141 offset:1024
	ds_read_b128 v[170:173], v141 offset:2048
	ds_read_b128 v[174:177], v141 offset:3072
	s_add_i32 s47, s64, s82
	s_add_i32 s84, s47, 0x100
	s_add_i32 s83, s11, s82
	s_cmpk_eq_i32 s82, 0xf00
	s_cselect_b32 s83, s80, s83
	s_cselect_b32 s84, s79, s84
	s_add_i32 s85, s47, 0x80
	s_mov_b32 m0, s71
	ds_read_b128 v[178:181], v140
	ds_read_b128 v[182:185], v140 offset:1024
	buffer_load_dwordx4 v135, s[12:15], s85 offen lds
	s_mov_b32 m0, s72
	ds_read_b128 v[186:189], v140 offset:2048
	ds_read_b128 v[190:193], v140 offset:3072
	buffer_load_dwordx4 v137, s[12:15], s85 offen lds
	s_add_i32 s47, s47, 0x80080
	s_mov_b32 m0, s73
	ds_read_b128 v[194:197], v140 offset:4096
	ds_read_b128 v[198:201], v140 offset:5120
	buffer_load_dwordx4 v135, s[12:15], s47 offen lds
	s_mov_b32 m0, s74
	ds_read_b128 v[202:205], v140 offset:6144
	ds_read_b128 v[206:209], v140 offset:7168
	buffer_load_dwordx4 v137, s[12:15], s47 offen lds
	s_waitcnt vmcnt(8)
	s_waitcnt lgkmcnt(0)
	s_barrier
	s_setprio 1
	s_waitcnt lgkmcnt(0)
	v_mfma_f32_16x16x32_bf16 v[126:129], v[142:145], v[178:181], v[126:129]
	v_mfma_f32_16x16x32_bf16 v[126:129], v[146:149], v[182:185], v[126:129]
	v_mfma_f32_16x16x32_bf16 v[110:113], v[142:145], v[186:189], v[110:113]
	v_mfma_f32_16x16x32_bf16 v[110:113], v[146:149], v[190:193], v[110:113]
	v_mfma_f32_16x16x32_bf16 v[94:97], v[142:145], v[194:197], v[94:97]
	v_mfma_f32_16x16x32_bf16 v[94:97], v[146:149], v[198:201], v[94:97]
	v_mfma_f32_16x16x32_bf16 v[78:81], v[142:145], v[202:205], v[78:81]
	v_mfma_f32_16x16x32_bf16 v[78:81], v[146:149], v[206:209], v[78:81]
	v_mfma_f32_16x16x32_bf16 v[122:125], v[154:157], v[178:181], v[122:125]
	v_mfma_f32_16x16x32_bf16 v[122:125], v[158:161], v[182:185], v[122:125]
	v_mfma_f32_16x16x32_bf16 v[106:109], v[154:157], v[186:189], v[106:109]
	v_mfma_f32_16x16x32_bf16 v[106:109], v[158:161], v[190:193], v[106:109]
	v_mfma_f32_16x16x32_bf16 v[90:93], v[154:157], v[194:197], v[90:93]
	v_mfma_f32_16x16x32_bf16 v[90:93], v[158:161], v[198:201], v[90:93]
	v_mfma_f32_16x16x32_bf16 v[74:77], v[154:157], v[202:205], v[74:77]
	v_mfma_f32_16x16x32_bf16 v[74:77], v[158:161], v[206:209], v[74:77]
	v_mfma_f32_16x16x32_bf16 v[118:121], v[162:165], v[178:181], v[118:121]
	v_mfma_f32_16x16x32_bf16 v[118:121], v[166:169], v[182:185], v[118:121]
	v_mfma_f32_16x16x32_bf16 v[102:105], v[162:165], v[186:189], v[102:105]
	v_mfma_f32_16x16x32_bf16 v[102:105], v[166:169], v[190:193], v[102:105]
	v_mfma_f32_16x16x32_bf16 v[86:89], v[162:165], v[194:197], v[86:89]
	v_mfma_f32_16x16x32_bf16 v[86:89], v[166:169], v[198:201], v[86:89]
	v_mfma_f32_16x16x32_bf16 v[70:73], v[162:165], v[202:205], v[70:73]
	v_mfma_f32_16x16x32_bf16 v[70:73], v[166:169], v[206:209], v[70:73]
	v_mfma_f32_16x16x32_bf16 v[114:117], v[170:173], v[178:181], v[114:117]
	v_mfma_f32_16x16x32_bf16 v[114:117], v[174:177], v[182:185], v[114:117]
	v_mfma_f32_16x16x32_bf16 v[98:101], v[170:173], v[186:189], v[98:101]
	v_mfma_f32_16x16x32_bf16 v[98:101], v[174:177], v[190:193], v[98:101]
	v_mfma_f32_16x16x32_bf16 v[82:85], v[170:173], v[194:197], v[82:85]
	v_mfma_f32_16x16x32_bf16 v[82:85], v[174:177], v[198:201], v[82:85]
	v_mfma_f32_16x16x32_bf16 v[66:69], v[170:173], v[202:205], v[66:69]
	v_mfma_f32_16x16x32_bf16 v[66:69], v[174:177], v[206:209], v[66:69]
	s_setprio 0
	s_barrier
	s_mov_b32 m0, s58
	s_mov_b32 s47, s15
	ds_read_b128 v[178:181], v140 offset:16384
	ds_read_b128 v[182:185], v140 offset:17408
	buffer_load_dwordx4 v136, s[44:47], s83 offen lds
	s_mov_b32 m0, s60
	ds_read_b128 v[186:189], v140 offset:18432
	ds_read_b128 v[190:193], v140 offset:19456
	buffer_load_dwordx4 v138, s[44:47], s83 offen lds
	s_add_i32 s85, s83, 0x80000
	s_mov_b32 m0, s61
	ds_read_b128 v[194:197], v140 offset:20480
	ds_read_b128 v[198:201], v140 offset:21504
	buffer_load_dwordx4 v136, s[44:47], s85 offen lds
	s_mov_b32 m0, s62
	ds_read_b128 v[202:205], v140 offset:22528
	ds_read_b128 v[206:209], v140 offset:23552
	buffer_load_dwordx4 v138, s[44:47], s85 offen lds
	s_waitcnt vmcnt(6)
	s_waitcnt lgkmcnt(0)
	s_barrier
	s_setprio 1
	s_waitcnt lgkmcnt(0)
	v_mfma_f32_16x16x32_bf16 v[62:65], v[142:145], v[178:181], v[62:65]
	v_mfma_f32_16x16x32_bf16 v[62:65], v[146:149], v[182:185], v[62:65]
	v_mfma_f32_16x16x32_bf16 v[46:49], v[142:145], v[186:189], v[46:49]
	v_mfma_f32_16x16x32_bf16 v[46:49], v[146:149], v[190:193], v[46:49]
	v_mfma_f32_16x16x32_bf16 v[30:33], v[142:145], v[194:197], v[30:33]
	v_mfma_f32_16x16x32_bf16 v[30:33], v[146:149], v[198:201], v[30:33]
	v_mfma_f32_16x16x32_bf16 v[14:17], v[142:145], v[202:205], v[14:17]
	v_mfma_f32_16x16x32_bf16 v[14:17], v[146:149], v[206:209], v[14:17]
	v_mfma_f32_16x16x32_bf16 v[58:61], v[154:157], v[178:181], v[58:61]
	v_mfma_f32_16x16x32_bf16 v[58:61], v[158:161], v[182:185], v[58:61]
	v_mfma_f32_16x16x32_bf16 v[42:45], v[154:157], v[186:189], v[42:45]
	v_mfma_f32_16x16x32_bf16 v[42:45], v[158:161], v[190:193], v[42:45]
	v_mfma_f32_16x16x32_bf16 v[26:29], v[154:157], v[194:197], v[26:29]
	v_mfma_f32_16x16x32_bf16 v[26:29], v[158:161], v[198:201], v[26:29]
	v_mfma_f32_16x16x32_bf16 v[10:13], v[154:157], v[202:205], v[10:13]
	v_mfma_f32_16x16x32_bf16 v[10:13], v[158:161], v[206:209], v[10:13]
	v_mfma_f32_16x16x32_bf16 v[54:57], v[162:165], v[178:181], v[54:57]
	v_mfma_f32_16x16x32_bf16 v[54:57], v[166:169], v[182:185], v[54:57]
	v_mfma_f32_16x16x32_bf16 v[38:41], v[162:165], v[186:189], v[38:41]
	v_mfma_f32_16x16x32_bf16 v[38:41], v[166:169], v[190:193], v[38:41]
	v_mfma_f32_16x16x32_bf16 v[22:25], v[162:165], v[194:197], v[22:25]
	v_mfma_f32_16x16x32_bf16 v[22:25], v[166:169], v[198:201], v[22:25]
	v_mfma_f32_16x16x32_bf16 v[6:9], v[162:165], v[202:205], v[6:9]
	v_mfma_f32_16x16x32_bf16 v[6:9], v[166:169], v[206:209], v[6:9]
	v_mfma_f32_16x16x32_bf16 v[50:53], v[170:173], v[178:181], v[50:53]
	v_mfma_f32_16x16x32_bf16 v[50:53], v[174:177], v[182:185], v[50:53]
	v_mfma_f32_16x16x32_bf16 v[34:37], v[170:173], v[186:189], v[34:37]
	v_mfma_f32_16x16x32_bf16 v[34:37], v[174:177], v[190:193], v[34:37]
	v_mfma_f32_16x16x32_bf16 v[18:21], v[170:173], v[194:197], v[18:21]
	v_mfma_f32_16x16x32_bf16 v[18:21], v[174:177], v[198:201], v[18:21]
	v_mfma_f32_16x16x32_bf16 v[2:5], v[170:173], v[202:205], v[2:5]
	v_mfma_f32_16x16x32_bf16 v[2:5], v[174:177], v[206:209], v[2:5]
	s_setprio 0
	s_barrier
	v_add_u32_e32 v141, 0x18000, v139
	ds_read_b128 v[142:145], v141
	ds_read_b128 v[146:149], v141 offset:1024
	ds_read_b128 v[154:157], v141 offset:2048
	ds_read_b128 v[158:161], v141 offset:3072
	v_add_u32_e32 v141, 0x1c000, v139
	ds_read_b128 v[162:165], v141
	ds_read_b128 v[166:169], v141 offset:1024
	ds_read_b128 v[170:173], v141 offset:2048
	ds_read_b128 v[174:177], v141 offset:3072
	s_mov_b32 m0, s51
	ds_read_b128 v[178:181], v140 offset:32768
	ds_read_b128 v[182:185], v140 offset:33792
	buffer_load_dwordx4 v135, s[12:15], s84 offen lds
	s_mov_b32 m0, s63
	ds_read_b128 v[186:189], v140 offset:34816
	ds_read_b128 v[190:193], v140 offset:35840
	buffer_load_dwordx4 v137, s[12:15], s84 offen lds
	s_add_i32 s84, s84, 0x80000
	s_mov_b32 m0, s65
	ds_read_b128 v[194:197], v140 offset:36864
	ds_read_b128 v[198:201], v140 offset:37888
	buffer_load_dwordx4 v135, s[12:15], s84 offen lds
	s_mov_b32 m0, s66
	ds_read_b128 v[202:205], v140 offset:38912
	ds_read_b128 v[206:209], v140 offset:39936
	buffer_load_dwordx4 v137, s[12:15], s84 offen lds
	s_waitcnt vmcnt(8)
	s_waitcnt lgkmcnt(0)
	s_barrier
	s_setprio 1
	s_waitcnt lgkmcnt(0)
	v_mfma_f32_16x16x32_bf16 v[126:129], v[142:145], v[178:181], v[126:129]
	v_mfma_f32_16x16x32_bf16 v[126:129], v[146:149], v[182:185], v[126:129]
	v_mfma_f32_16x16x32_bf16 v[110:113], v[142:145], v[186:189], v[110:113]
	v_mfma_f32_16x16x32_bf16 v[110:113], v[146:149], v[190:193], v[110:113]
	v_mfma_f32_16x16x32_bf16 v[94:97], v[142:145], v[194:197], v[94:97]
	v_mfma_f32_16x16x32_bf16 v[94:97], v[146:149], v[198:201], v[94:97]
	v_mfma_f32_16x16x32_bf16 v[78:81], v[142:145], v[202:205], v[78:81]
	v_mfma_f32_16x16x32_bf16 v[78:81], v[146:149], v[206:209], v[78:81]
	v_mfma_f32_16x16x32_bf16 v[122:125], v[154:157], v[178:181], v[122:125]
	v_mfma_f32_16x16x32_bf16 v[122:125], v[158:161], v[182:185], v[122:125]
	v_mfma_f32_16x16x32_bf16 v[106:109], v[154:157], v[186:189], v[106:109]
	v_mfma_f32_16x16x32_bf16 v[106:109], v[158:161], v[190:193], v[106:109]
	v_mfma_f32_16x16x32_bf16 v[90:93], v[154:157], v[194:197], v[90:93]
	v_mfma_f32_16x16x32_bf16 v[90:93], v[158:161], v[198:201], v[90:93]
	v_mfma_f32_16x16x32_bf16 v[74:77], v[154:157], v[202:205], v[74:77]
	v_mfma_f32_16x16x32_bf16 v[74:77], v[158:161], v[206:209], v[74:77]
	v_mfma_f32_16x16x32_bf16 v[118:121], v[162:165], v[178:181], v[118:121]
	v_mfma_f32_16x16x32_bf16 v[118:121], v[166:169], v[182:185], v[118:121]
	v_mfma_f32_16x16x32_bf16 v[102:105], v[162:165], v[186:189], v[102:105]
	v_mfma_f32_16x16x32_bf16 v[102:105], v[166:169], v[190:193], v[102:105]
	v_mfma_f32_16x16x32_bf16 v[86:89], v[162:165], v[194:197], v[86:89]
	v_mfma_f32_16x16x32_bf16 v[86:89], v[166:169], v[198:201], v[86:89]
	v_mfma_f32_16x16x32_bf16 v[70:73], v[162:165], v[202:205], v[70:73]
	v_mfma_f32_16x16x32_bf16 v[70:73], v[166:169], v[206:209], v[70:73]
	v_mfma_f32_16x16x32_bf16 v[114:117], v[170:173], v[178:181], v[114:117]
	v_mfma_f32_16x16x32_bf16 v[114:117], v[174:177], v[182:185], v[114:117]
	v_mfma_f32_16x16x32_bf16 v[98:101], v[170:173], v[186:189], v[98:101]
	v_mfma_f32_16x16x32_bf16 v[98:101], v[174:177], v[190:193], v[98:101]
	v_mfma_f32_16x16x32_bf16 v[82:85], v[170:173], v[194:197], v[82:85]
	v_mfma_f32_16x16x32_bf16 v[82:85], v[174:177], v[198:201], v[82:85]
	v_mfma_f32_16x16x32_bf16 v[66:69], v[170:173], v[202:205], v[66:69]
	v_mfma_f32_16x16x32_bf16 v[66:69], v[174:177], v[206:209], v[66:69]
	s_setprio 0
	s_barrier
	s_mov_b32 m0, s67
	s_or_b32 s84, s83, 0x80
	ds_read_b128 v[178:181], v140 offset:49152
	ds_read_b128 v[182:185], v140 offset:50176
	buffer_load_dwordx4 v136, s[44:47], s84 offen lds
	s_mov_b32 m0, s68
	ds_read_b128 v[186:189], v140 offset:51200
	ds_read_b128 v[190:193], v140 offset:52224
	buffer_load_dwordx4 v138, s[44:47], s84 offen lds
	s_add_i32 s83, s83, 0x80080
	s_mov_b32 m0, s69
	ds_read_b128 v[194:197], v140 offset:53248
	ds_read_b128 v[198:201], v140 offset:54272
	buffer_load_dwordx4 v136, s[44:47], s83 offen lds
	s_mov_b32 m0, s70
	ds_read_b128 v[202:205], v140 offset:55296
	ds_read_b128 v[206:209], v140 offset:56320
	buffer_load_dwordx4 v138, s[44:47], s83 offen lds
	s_waitcnt vmcnt(6)
	s_waitcnt lgkmcnt(0)
	s_barrier
	s_setprio 1
	s_waitcnt lgkmcnt(0)
	v_mfma_f32_16x16x32_bf16 v[62:65], v[142:145], v[178:181], v[62:65]
	v_mfma_f32_16x16x32_bf16 v[62:65], v[146:149], v[182:185], v[62:65]
	v_mfma_f32_16x16x32_bf16 v[46:49], v[142:145], v[186:189], v[46:49]
	v_mfma_f32_16x16x32_bf16 v[46:49], v[146:149], v[190:193], v[46:49]
	v_mfma_f32_16x16x32_bf16 v[30:33], v[142:145], v[194:197], v[30:33]
	v_mfma_f32_16x16x32_bf16 v[30:33], v[146:149], v[198:201], v[30:33]
	v_mfma_f32_16x16x32_bf16 v[14:17], v[142:145], v[202:205], v[14:17]
	v_mfma_f32_16x16x32_bf16 v[14:17], v[146:149], v[206:209], v[14:17]
	v_mfma_f32_16x16x32_bf16 v[58:61], v[154:157], v[178:181], v[58:61]
	v_mfma_f32_16x16x32_bf16 v[58:61], v[158:161], v[182:185], v[58:61]
	v_mfma_f32_16x16x32_bf16 v[42:45], v[154:157], v[186:189], v[42:45]
	v_mfma_f32_16x16x32_bf16 v[42:45], v[158:161], v[190:193], v[42:45]
	v_mfma_f32_16x16x32_bf16 v[26:29], v[154:157], v[194:197], v[26:29]
	v_mfma_f32_16x16x32_bf16 v[26:29], v[158:161], v[198:201], v[26:29]
	v_mfma_f32_16x16x32_bf16 v[10:13], v[154:157], v[202:205], v[10:13]
	v_mfma_f32_16x16x32_bf16 v[10:13], v[158:161], v[206:209], v[10:13]
	v_mfma_f32_16x16x32_bf16 v[54:57], v[162:165], v[178:181], v[54:57]
	v_mfma_f32_16x16x32_bf16 v[54:57], v[166:169], v[182:185], v[54:57]
	v_mfma_f32_16x16x32_bf16 v[38:41], v[162:165], v[186:189], v[38:41]
	v_mfma_f32_16x16x32_bf16 v[38:41], v[166:169], v[190:193], v[38:41]
	v_mfma_f32_16x16x32_bf16 v[22:25], v[162:165], v[194:197], v[22:25]
	v_mfma_f32_16x16x32_bf16 v[22:25], v[166:169], v[198:201], v[22:25]
	v_mfma_f32_16x16x32_bf16 v[6:9], v[162:165], v[202:205], v[6:9]
	v_mfma_f32_16x16x32_bf16 v[6:9], v[166:169], v[206:209], v[6:9]
	v_mfma_f32_16x16x32_bf16 v[50:53], v[170:173], v[178:181], v[50:53]
	v_mfma_f32_16x16x32_bf16 v[50:53], v[174:177], v[182:185], v[50:53]
	v_mfma_f32_16x16x32_bf16 v[34:37], v[170:173], v[186:189], v[34:37]
	v_mfma_f32_16x16x32_bf16 v[34:37], v[174:177], v[190:193], v[34:37]
	v_mfma_f32_16x16x32_bf16 v[18:21], v[170:173], v[194:197], v[18:21]
	v_mfma_f32_16x16x32_bf16 v[18:21], v[174:177], v[198:201], v[18:21]
	v_mfma_f32_16x16x32_bf16 v[2:5], v[170:173], v[202:205], v[2:5]
	v_mfma_f32_16x16x32_bf16 v[2:5], v[174:177], v[206:209], v[2:5]
	s_setprio 0
	s_barrier
	s_add_i32 s81, s81, 2
	s_addk_i32 s82, 0x100
	s_cmp_gt_u32 s81, 29
	s_cbranch_scc0 .LBB0_605
	s_andn2_b64 vcc, exec, s[4:5]
	s_cbranch_vccnz .LBB0_597
	v_mov_b32_e32 v2, 0
	s_mov_b32 s42, s77
	s_mov_b32 s3, s78
	s_mov_b32 s59, s10
	s_mov_b32 s64, s9
	s_mov_b32 s75, s8
	v_mov_b32_e32 v3, v2
	v_mov_b32_e32 v4, v2
	v_mov_b32_e32 v5, v2
	v_mov_b32_e32 v6, v2
	v_mov_b32_e32 v7, v2
	v_mov_b32_e32 v8, v2
	v_mov_b32_e32 v9, v2
	v_mov_b32_e32 v18, v2
	v_mov_b32_e32 v19, v2
	v_mov_b32_e32 v20, v2
	v_mov_b32_e32 v21, v2
	v_mov_b32_e32 v22, v2
	v_mov_b32_e32 v23, v2
	v_mov_b32_e32 v24, v2
	v_mov_b32_e32 v25, v2
	v_mov_b32_e32 v34, v2
	v_mov_b32_e32 v35, v2
	v_mov_b32_e32 v36, v2
	v_mov_b32_e32 v37, v2
	v_mov_b32_e32 v38, v2
	v_mov_b32_e32 v39, v2
	v_mov_b32_e32 v40, v2
	v_mov_b32_e32 v41, v2
	v_mov_b32_e32 v50, v2
	v_mov_b32_e32 v51, v2
	v_mov_b32_e32 v52, v2
	v_mov_b32_e32 v53, v2
	v_mov_b32_e32 v54, v2
	v_mov_b32_e32 v55, v2
	v_mov_b32_e32 v56, v2
	v_mov_b32_e32 v57, v2
	v_mov_b32_e32 v10, v2
	v_mov_b32_e32 v11, v2
	v_mov_b32_e32 v12, v2
	v_mov_b32_e32 v13, v2
	v_mov_b32_e32 v14, v2
	v_mov_b32_e32 v15, v2
	v_mov_b32_e32 v16, v2
	v_mov_b32_e32 v17, v2
	v_mov_b32_e32 v26, v2
	v_mov_b32_e32 v27, v2
	v_mov_b32_e32 v28, v2
	v_mov_b32_e32 v29, v2
	v_mov_b32_e32 v30, v2
	v_mov_b32_e32 v31, v2
	v_mov_b32_e32 v32, v2
	v_mov_b32_e32 v33, v2
	v_mov_b32_e32 v42, v2
	v_mov_b32_e32 v43, v2
	v_mov_b32_e32 v44, v2
	v_mov_b32_e32 v45, v2
	v_mov_b32_e32 v46, v2
	v_mov_b32_e32 v47, v2
	v_mov_b32_e32 v48, v2
	v_mov_b32_e32 v49, v2
	v_mov_b32_e32 v58, v2
	v_mov_b32_e32 v59, v2
	v_mov_b32_e32 v60, v2
	v_mov_b32_e32 v61, v2
	v_mov_b32_e32 v62, v2
	v_mov_b32_e32 v63, v2
	v_mov_b32_e32 v64, v2
	v_mov_b32_e32 v65, v2
	v_mov_b32_e32 v66, v2
	v_mov_b32_e32 v67, v2
	v_mov_b32_e32 v68, v2
	v_mov_b32_e32 v69, v2
	v_mov_b32_e32 v70, v2
	v_mov_b32_e32 v71, v2
	v_mov_b32_e32 v72, v2
	v_mov_b32_e32 v73, v2
	v_mov_b32_e32 v82, v2
	v_mov_b32_e32 v83, v2
	v_mov_b32_e32 v84, v2
	v_mov_b32_e32 v85, v2
	v_mov_b32_e32 v86, v2
	v_mov_b32_e32 v87, v2
	v_mov_b32_e32 v88, v2
	v_mov_b32_e32 v89, v2
	v_mov_b32_e32 v98, v2
	v_mov_b32_e32 v99, v2
	v_mov_b32_e32 v100, v2
	v_mov_b32_e32 v101, v2
	v_mov_b32_e32 v102, v2
	v_mov_b32_e32 v103, v2
	v_mov_b32_e32 v104, v2
	v_mov_b32_e32 v105, v2
	v_mov_b32_e32 v114, v2
	v_mov_b32_e32 v115, v2
	v_mov_b32_e32 v116, v2
	v_mov_b32_e32 v117, v2
	v_mov_b32_e32 v118, v2
	v_mov_b32_e32 v119, v2
	v_mov_b32_e32 v120, v2
	v_mov_b32_e32 v121, v2
	v_mov_b32_e32 v74, v2
	v_mov_b32_e32 v75, v2
	v_mov_b32_e32 v76, v2
	v_mov_b32_e32 v77, v2
	v_mov_b32_e32 v78, v2
	v_mov_b32_e32 v79, v2
	v_mov_b32_e32 v80, v2
	v_mov_b32_e32 v81, v2
	v_mov_b32_e32 v90, v2
	v_mov_b32_e32 v91, v2
	v_mov_b32_e32 v92, v2
	v_mov_b32_e32 v93, v2
	v_mov_b32_e32 v94, v2
	v_mov_b32_e32 v95, v2
	v_mov_b32_e32 v96, v2
	v_mov_b32_e32 v97, v2
	v_mov_b32_e32 v106, v2
	v_mov_b32_e32 v107, v2
	v_mov_b32_e32 v108, v2
	v_mov_b32_e32 v109, v2
	v_mov_b32_e32 v110, v2
	v_mov_b32_e32 v111, v2
	v_mov_b32_e32 v112, v2
	v_mov_b32_e32 v113, v2
	v_mov_b32_e32 v122, v2
	v_mov_b32_e32 v123, v2
	v_mov_b32_e32 v124, v2
	v_mov_b32_e32 v125, v2
	v_mov_b32_e32 v126, v2
	v_mov_b32_e32 v127, v2
	v_mov_b32_e32 v128, v2
	v_mov_b32_e32 v129, v2
	s_branch .LBB0_597

.LBB0_822:
	ds_read_b128 v[66:69], v242
	ds_read_b128 v[70:73], v242 offset:1024
	ds_read_b128 v[74:77], v242 offset:2048
	ds_read_b128 v[78:81], v242 offset:3072
	ds_read_b128 v[82:85], v243
	ds_read_b128 v[86:89], v243 offset:1024
	ds_read_b128 v[90:93], v243 offset:2048
	ds_read_b128 v[94:97], v243 offset:3072
	s_add_i32 s43, s68, 0xfff80080
	s_cmp_eq_u32 s69, 28
	s_cselect_b32 s91, s11, s67
	s_cselect_b32 s92, s10, s43
	s_add_i32 s43, s68, 0xfff80000
	s_mov_b32 m0, s79
	ds_read_b128 v[98:101], v244
	ds_read_b128 v[102:105], v244 offset:1024
	buffer_load_dwordx4 v1, s[48:51], s43 offen lds
	s_mov_b32 m0, s80
	ds_read_b128 v[106:109], v244 offset:2048
	ds_read_b128 v[110:113], v244 offset:3072
	buffer_load_dwordx4 v236, s[48:51], s43 offen lds
	s_mov_b32 m0, s81
	ds_read_b128 v[114:117], v244 offset:4096
	ds_read_b128 v[118:121], v244 offset:5120
	buffer_load_dwordx4 v1, s[48:51], s68 offen lds
	s_mov_b32 m0, s82
	ds_read_b128 v[122:125], v244 offset:6144
	ds_read_b128 v[126:129], v244 offset:7168
	buffer_load_dwordx4 v236, s[48:51], s68 offen lds
	s_waitcnt vmcnt(8)
	s_waitcnt lgkmcnt(0)
	s_barrier
	s_setprio 1
	s_waitcnt lgkmcnt(0)
	v_mfma_f32_16x16x32_bf16 v[190:193], v[66:69], v[98:101], v[190:193]
	v_mfma_f32_16x16x32_bf16 v[190:193], v[70:73], v[102:105], v[190:193]
	v_mfma_f32_16x16x32_bf16 v[174:177], v[66:69], v[106:109], v[174:177]
	v_mfma_f32_16x16x32_bf16 v[174:177], v[70:73], v[110:113], v[174:177]
	v_mfma_f32_16x16x32_bf16 v[170:173], v[66:69], v[114:117], v[170:173]
	v_mfma_f32_16x16x32_bf16 v[170:173], v[70:73], v[118:121], v[170:173]
	v_mfma_f32_16x16x32_bf16 v[158:161], v[66:69], v[122:125], v[158:161]
	v_mfma_f32_16x16x32_bf16 v[158:161], v[70:73], v[126:129], v[158:161]
	v_mfma_f32_16x16x32_bf16 v[186:189], v[74:77], v[98:101], v[186:189]
	v_mfma_f32_16x16x32_bf16 v[186:189], v[78:81], v[102:105], v[186:189]
	v_mfma_f32_16x16x32_bf16 v[166:169], v[74:77], v[106:109], v[166:169]
	v_mfma_f32_16x16x32_bf16 v[166:169], v[78:81], v[110:113], v[166:169]
	v_mfma_f32_16x16x32_bf16 v[162:165], v[74:77], v[114:117], v[162:165]
	v_mfma_f32_16x16x32_bf16 v[162:165], v[78:81], v[118:121], v[162:165]
	v_mfma_f32_16x16x32_bf16 v[154:157], v[74:77], v[122:125], v[154:157]
	v_mfma_f32_16x16x32_bf16 v[154:157], v[78:81], v[126:129], v[154:157]
	v_mfma_f32_16x16x32_bf16 v[182:185], v[82:85], v[98:101], v[182:185]
	v_mfma_f32_16x16x32_bf16 v[182:185], v[86:89], v[102:105], v[182:185]
	v_mfma_f32_16x16x32_bf16 v[98:101], v[90:93], v[98:101], v[178:181]
	v_mfma_f32_16x16x32_bf16 v[98:101], v[94:97], v[102:105], v[98:101]
	v_mfma_f32_16x16x32_bf16 v[102:105], v[82:85], v[106:109], v[150:153]
	v_mfma_f32_16x16x32_bf16 v[102:105], v[86:89], v[110:113], v[102:105]
	v_mfma_f32_16x16x32_bf16 v[106:109], v[90:93], v[106:109], v[142:145]
	v_mfma_f32_16x16x32_bf16 v[106:109], v[94:97], v[110:113], v[106:109]
	v_mfma_f32_16x16x32_bf16 v[110:113], v[82:85], v[114:117], v[146:149]
	v_mfma_f32_16x16x32_bf16 v[110:113], v[86:89], v[118:121], v[110:113]
	v_mfma_f32_16x16x32_bf16 v[114:117], v[90:93], v[114:117], v[138:141]
	v_mfma_f32_16x16x32_bf16 v[114:117], v[94:97], v[118:121], v[114:117]
	v_mfma_f32_16x16x32_bf16 v[118:121], v[82:85], v[122:125], v[134:137]
	v_mfma_f32_16x16x32_bf16 v[118:121], v[86:89], v[126:129], v[118:121]
	v_mfma_f32_16x16x32_bf16 v[122:125], v[90:93], v[122:125], v[130:133]
	v_mfma_f32_16x16x32_bf16 v[122:125], v[94:97], v[126:129], v[122:125]
	s_setprio 0
	s_barrier
	s_mov_b32 m0, s29
	s_mov_b32 s43, s51
	ds_read_b128 v[126:129], v244 offset:16384
	ds_read_b128 v[130:133], v244 offset:17408
	buffer_load_dwordx4 v227, s[40:43], s91 offen lds
	s_mov_b32 m0, s35
	ds_read_b128 v[134:137], v244 offset:18432
	ds_read_b128 v[138:141], v244 offset:19456
	buffer_load_dwordx4 v237, s[40:43], s91 offen lds
	s_add_i32 s93, s91, 0x1600000
	s_mov_b32 m0, s63
	ds_read_b128 v[142:145], v244 offset:20480
	ds_read_b128 v[146:149], v244 offset:21504
	buffer_load_dwordx4 v227, s[40:43], s93 offen lds
	s_mov_b32 m0, s65
	ds_read_b128 v[150:153], v244 offset:22528
	ds_read_b128 v[178:181], v244 offset:23552
	buffer_load_dwordx4 v237, s[40:43], s93 offen lds
	s_waitcnt vmcnt(6)
	s_waitcnt lgkmcnt(0)
	s_barrier
	s_setprio 1
	s_waitcnt lgkmcnt(0)
	v_mfma_f32_16x16x32_bf16 v[62:65], v[66:69], v[126:129], v[62:65]
	v_mfma_f32_16x16x32_bf16 v[62:65], v[70:73], v[130:133], v[62:65]
	v_mfma_f32_16x16x32_bf16 v[46:49], v[66:69], v[134:137], v[46:49]
	v_mfma_f32_16x16x32_bf16 v[46:49], v[70:73], v[138:141], v[46:49]
	v_mfma_f32_16x16x32_bf16 v[42:45], v[66:69], v[142:145], v[42:45]
	v_mfma_f32_16x16x32_bf16 v[42:45], v[70:73], v[146:149], v[42:45]
	v_mfma_f32_16x16x32_bf16 v[30:33], v[66:69], v[150:153], v[30:33]
	v_mfma_f32_16x16x32_bf16 v[30:33], v[70:73], v[178:181], v[30:33]
	v_mfma_f32_16x16x32_bf16 v[58:61], v[74:77], v[126:129], v[58:61]
	v_mfma_f32_16x16x32_bf16 v[58:61], v[78:81], v[130:133], v[58:61]
	v_mfma_f32_16x16x32_bf16 v[38:41], v[74:77], v[134:137], v[38:41]
	v_mfma_f32_16x16x32_bf16 v[38:41], v[78:81], v[138:141], v[38:41]
	v_mfma_f32_16x16x32_bf16 v[34:37], v[74:77], v[142:145], v[34:37]
	v_mfma_f32_16x16x32_bf16 v[34:37], v[78:81], v[146:149], v[34:37]
	v_mfma_f32_16x16x32_bf16 v[26:29], v[74:77], v[150:153], v[26:29]
	v_mfma_f32_16x16x32_bf16 v[26:29], v[78:81], v[178:181], v[26:29]
	v_mfma_f32_16x16x32_bf16 v[54:57], v[82:85], v[126:129], v[54:57]
	v_mfma_f32_16x16x32_bf16 v[54:57], v[86:89], v[130:133], v[54:57]
	v_mfma_f32_16x16x32_bf16 v[22:25], v[82:85], v[134:137], v[22:25]
	v_mfma_f32_16x16x32_bf16 v[22:25], v[86:89], v[138:141], v[22:25]
	v_mfma_f32_16x16x32_bf16 v[18:21], v[82:85], v[142:145], v[18:21]
	v_mfma_f32_16x16x32_bf16 v[18:21], v[86:89], v[146:149], v[18:21]
	v_mfma_f32_16x16x32_bf16 v[6:9], v[82:85], v[150:153], v[6:9]
	v_mfma_f32_16x16x32_bf16 v[6:9], v[86:89], v[178:181], v[6:9]
	v_mfma_f32_16x16x32_bf16 v[50:53], v[90:93], v[126:129], v[50:53]
	v_mfma_f32_16x16x32_bf16 v[50:53], v[94:97], v[130:133], v[50:53]
	v_mfma_f32_16x16x32_bf16 v[14:17], v[90:93], v[134:137], v[14:17]
	v_mfma_f32_16x16x32_bf16 v[14:17], v[94:97], v[138:141], v[14:17]
	v_mfma_f32_16x16x32_bf16 v[10:13], v[90:93], v[142:145], v[10:13]
	v_mfma_f32_16x16x32_bf16 v[10:13], v[94:97], v[146:149], v[10:13]
	v_mfma_f32_16x16x32_bf16 v[2:5], v[90:93], v[150:153], v[2:5]
	v_mfma_f32_16x16x32_bf16 v[2:5], v[94:97], v[178:181], v[2:5]
	s_setprio 0
	s_barrier
	ds_read_b128 v[66:69], v245
	ds_read_b128 v[70:73], v245 offset:1024
	ds_read_b128 v[74:77], v245 offset:2048
	ds_read_b128 v[78:81], v245 offset:3072
	ds_read_b128 v[82:85], v246
	ds_read_b128 v[86:89], v246 offset:1024
	ds_read_b128 v[90:93], v246 offset:2048
	ds_read_b128 v[94:97], v246 offset:3072
	s_mov_b32 m0, s3
	ds_read_b128 v[126:129], v244 offset:32768
	ds_read_b128 v[130:133], v244 offset:33792
	buffer_load_dwordx4 v1, s[48:51], s92 offen lds
	s_mov_b32 m0, s70
	ds_read_b128 v[134:137], v244 offset:34816
	ds_read_b128 v[138:141], v244 offset:35840
	buffer_load_dwordx4 v236, s[48:51], s92 offen lds
	s_add_i32 s92, s92, 0x80000
	s_mov_b32 m0, s71
	ds_read_b128 v[194:197], v244 offset:36864
	ds_read_b128 v[198:201], v244 offset:37888
	buffer_load_dwordx4 v1, s[48:51], s92 offen lds
	s_mov_b32 m0, s72
	ds_read_b128 v[202:205], v244 offset:38912
	ds_read_b128 v[206:209], v244 offset:39936
	buffer_load_dwordx4 v236, s[48:51], s92 offen lds
	s_waitcnt vmcnt(8)
	s_waitcnt lgkmcnt(0)
	s_barrier
	s_setprio 1
	s_waitcnt lgkmcnt(0)
	v_mfma_f32_16x16x32_bf16 v[142:145], v[66:69], v[126:129], v[190:193]
	v_mfma_f32_16x16x32_bf16 v[190:193], v[70:73], v[130:133], v[142:145]
	v_mfma_f32_16x16x32_bf16 v[142:145], v[74:77], v[126:129], v[186:189]
	v_mfma_f32_16x16x32_bf16 v[186:189], v[78:81], v[130:133], v[142:145]
	v_mfma_f32_16x16x32_bf16 v[142:145], v[66:69], v[134:137], v[174:177]
	v_mfma_f32_16x16x32_bf16 v[174:177], v[70:73], v[138:141], v[142:145]
	v_mfma_f32_16x16x32_bf16 v[142:145], v[74:77], v[134:137], v[166:169]
	v_mfma_f32_16x16x32_bf16 v[166:169], v[78:81], v[138:141], v[142:145]
	v_mfma_f32_16x16x32_bf16 v[142:145], v[66:69], v[194:197], v[170:173]
	v_mfma_f32_16x16x32_bf16 v[170:173], v[70:73], v[198:201], v[142:145]
	v_mfma_f32_16x16x32_bf16 v[142:145], v[74:77], v[194:197], v[162:165]
	v_mfma_f32_16x16x32_bf16 v[162:165], v[78:81], v[198:201], v[142:145]
	v_mfma_f32_16x16x32_bf16 v[142:145], v[66:69], v[202:205], v[158:161]
	v_mfma_f32_16x16x32_bf16 v[158:161], v[70:73], v[206:209], v[142:145]
	v_mfma_f32_16x16x32_bf16 v[142:145], v[74:77], v[202:205], v[154:157]
	v_mfma_f32_16x16x32_bf16 v[154:157], v[78:81], v[206:209], v[142:145]
	v_mfma_f32_16x16x32_bf16 v[98:101], v[90:93], v[126:129], v[98:101]
	v_mfma_f32_16x16x32_bf16 v[178:181], v[94:97], v[130:133], v[98:101]
	v_mfma_f32_16x16x32_bf16 v[98:101], v[82:85], v[134:137], v[102:105]
	v_mfma_f32_16x16x32_bf16 v[150:153], v[86:89], v[138:141], v[98:101]
	v_mfma_f32_16x16x32_bf16 v[98:101], v[90:93], v[134:137], v[106:109]
	v_mfma_f32_16x16x32_bf16 v[142:145], v[82:85], v[126:129], v[182:185]
	v_mfma_f32_16x16x32_bf16 v[182:185], v[86:89], v[130:133], v[142:145]
	v_mfma_f32_16x16x32_bf16 v[142:145], v[94:97], v[138:141], v[98:101]
	v_mfma_f32_16x16x32_bf16 v[98:101], v[82:85], v[194:197], v[110:113]
	v_mfma_f32_16x16x32_bf16 v[146:149], v[86:89], v[198:201], v[98:101]
	v_mfma_f32_16x16x32_bf16 v[98:101], v[90:93], v[194:197], v[114:117]
	v_mfma_f32_16x16x32_bf16 v[138:141], v[94:97], v[198:201], v[98:101]
	v_mfma_f32_16x16x32_bf16 v[98:101], v[82:85], v[202:205], v[118:121]
	v_mfma_f32_16x16x32_bf16 v[134:137], v[86:89], v[206:209], v[98:101]
	v_mfma_f32_16x16x32_bf16 v[98:101], v[90:93], v[202:205], v[122:125]
	v_mfma_f32_16x16x32_bf16 v[130:133], v[94:97], v[206:209], v[98:101]
	s_setprio 0
	s_barrier
	s_mov_b32 m0, s74
	s_or_b32 s92, s91, 0x80
	s_nop 2
	ds_read_b128 v[98:101], v244 offset:49152
	ds_read_b128 v[102:105], v244 offset:50176
	buffer_load_dwordx4 v227, s[40:43], s92 offen lds
	s_mov_b32 m0, s75
	ds_read_b128 v[106:109], v244 offset:51200
	ds_read_b128 v[110:113], v244 offset:52224
	buffer_load_dwordx4 v237, s[40:43], s92 offen lds
	s_add_i32 s91, s91, 0x1600080
	s_mov_b32 m0, s77
	ds_read_b128 v[114:117], v244 offset:53248
	ds_read_b128 v[118:121], v244 offset:54272
	buffer_load_dwordx4 v227, s[40:43], s91 offen lds
	s_mov_b32 m0, s78
	ds_read_b128 v[122:125], v244 offset:55296
	ds_read_b128 v[126:129], v244 offset:56320
	buffer_load_dwordx4 v237, s[40:43], s91 offen lds
	s_waitcnt vmcnt(6)
	s_waitcnt lgkmcnt(0)
	s_barrier
	s_setprio 1
	s_waitcnt lgkmcnt(0)
	v_mfma_f32_16x16x32_bf16 v[62:65], v[66:69], v[98:101], v[62:65]
	v_mfma_f32_16x16x32_bf16 v[62:65], v[70:73], v[102:105], v[62:65]
	v_mfma_f32_16x16x32_bf16 v[46:49], v[66:69], v[106:109], v[46:49]
	v_mfma_f32_16x16x32_bf16 v[46:49], v[70:73], v[110:113], v[46:49]
	v_mfma_f32_16x16x32_bf16 v[42:45], v[66:69], v[114:117], v[42:45]
	v_mfma_f32_16x16x32_bf16 v[42:45], v[70:73], v[118:121], v[42:45]
	v_mfma_f32_16x16x32_bf16 v[30:33], v[66:69], v[122:125], v[30:33]
	v_mfma_f32_16x16x32_bf16 v[30:33], v[70:73], v[126:129], v[30:33]
	v_mfma_f32_16x16x32_bf16 v[58:61], v[74:77], v[98:101], v[58:61]
	v_mfma_f32_16x16x32_bf16 v[58:61], v[78:81], v[102:105], v[58:61]
	v_mfma_f32_16x16x32_bf16 v[38:41], v[74:77], v[106:109], v[38:41]
	v_mfma_f32_16x16x32_bf16 v[38:41], v[78:81], v[110:113], v[38:41]
	v_mfma_f32_16x16x32_bf16 v[34:37], v[74:77], v[114:117], v[34:37]
	v_mfma_f32_16x16x32_bf16 v[34:37], v[78:81], v[118:121], v[34:37]
	v_mfma_f32_16x16x32_bf16 v[26:29], v[74:77], v[122:125], v[26:29]
	v_mfma_f32_16x16x32_bf16 v[26:29], v[78:81], v[126:129], v[26:29]
	v_mfma_f32_16x16x32_bf16 v[54:57], v[82:85], v[98:101], v[54:57]
	v_mfma_f32_16x16x32_bf16 v[54:57], v[86:89], v[102:105], v[54:57]
	v_mfma_f32_16x16x32_bf16 v[22:25], v[82:85], v[106:109], v[22:25]
	v_mfma_f32_16x16x32_bf16 v[22:25], v[86:89], v[110:113], v[22:25]
	v_mfma_f32_16x16x32_bf16 v[18:21], v[82:85], v[114:117], v[18:21]
	v_mfma_f32_16x16x32_bf16 v[18:21], v[86:89], v[118:121], v[18:21]
	v_mfma_f32_16x16x32_bf16 v[6:9], v[82:85], v[122:125], v[6:9]
	v_mfma_f32_16x16x32_bf16 v[6:9], v[86:89], v[126:129], v[6:9]
	v_mfma_f32_16x16x32_bf16 v[50:53], v[90:93], v[98:101], v[50:53]
	v_mfma_f32_16x16x32_bf16 v[50:53], v[94:97], v[102:105], v[50:53]
	v_mfma_f32_16x16x32_bf16 v[14:17], v[90:93], v[106:109], v[14:17]
	v_mfma_f32_16x16x32_bf16 v[14:17], v[94:97], v[110:113], v[14:17]
	v_mfma_f32_16x16x32_bf16 v[10:13], v[90:93], v[114:117], v[10:13]
	v_mfma_f32_16x16x32_bf16 v[10:13], v[94:97], v[118:121], v[10:13]
	v_mfma_f32_16x16x32_bf16 v[2:5], v[90:93], v[122:125], v[2:5]
	v_mfma_f32_16x16x32_bf16 v[2:5], v[94:97], v[126:129], v[2:5]
	s_setprio 0
	s_barrier
	s_add_i32 s69, s69, 2
	s_addk_i32 s67, 0x100
	s_addk_i32 s68, 0x100
	s_cmp_gt_u32 s69, 29
	s_cbranch_scc0 .LBB0_822
	s_and_b64 vcc, exec, s[38:39]
	s_cbranch_vccz .LBB0_825
	s_barrier

.LBB0_1003:
	v_add_u32_e32 v130, 0x10000, v155
	ds_read_b128 v[132:135], v130
	ds_read_b128 v[144:147], v130 offset:1024
	ds_read_b128 v[158:161], v130 offset:2048
	ds_read_b128 v[162:165], v130 offset:3072
	v_add_u32_e32 v130, 0x14000, v155
	s_lshl_b32 s39, s92, 7
	ds_read_b128 v[166:169], v130
	ds_read_b128 v[170:173], v130 offset:1024
	ds_read_b128 v[174:177], v130 offset:2048
	ds_read_b128 v[178:181], v130 offset:3072
	s_add_i32 s93, s61, s39
	s_addk_i32 s39, 0x100
	s_add_i32 s94, s93, 0x80
	s_add_i32 s95, s39, s61
	s_and_b64 s[50:51], s[48:49], exec
	s_cselect_b32 s50, s87, s95
	s_add_i32 s39, s39, s63
	s_and_b64 s[48:49], s[48:49], exec
	s_cselect_b32 s48, s88, s39
	s_or_b32 s49, s48, 0x80
	s_mov_b32 m0, s77
	ds_read_b128 v[182:185], v156
	ds_read_b128 v[186:189], v156 offset:1024
	buffer_load_dwordx4 v151, s[28:31], s94 offen lds
	s_mov_b32 m0, s78
	ds_read_b128 v[190:193], v156 offset:2048
	ds_read_b128 v[194:197], v156 offset:3072
	buffer_load_dwordx4 v153, s[28:31], s94 offen lds
	s_add_i32 s93, s93, 0x160080
	s_mov_b32 m0, s79
	ds_read_b128 v[198:201], v156 offset:4096
	ds_read_b128 v[202:205], v156 offset:5120
	buffer_load_dwordx4 v151, s[28:31], s93 offen lds
	s_mov_b32 m0, s80
	ds_read_b128 v[206:209], v156 offset:6144
	ds_read_b128 v[210:213], v156 offset:7168
	buffer_load_dwordx4 v153, s[28:31], s93 offen lds
	s_waitcnt vmcnt(8)
	s_waitcnt lgkmcnt(0)
	s_barrier
	s_setprio 1
	s_waitcnt lgkmcnt(0)
	v_mfma_f32_16x16x32_bf16 v[126:129], v[132:135], v[182:185], v[126:129]
	v_mfma_f32_16x16x32_bf16 v[126:129], v[144:147], v[186:189], v[126:129]
	v_mfma_f32_16x16x32_bf16 v[110:113], v[132:135], v[190:193], v[110:113]
	v_mfma_f32_16x16x32_bf16 v[110:113], v[144:147], v[194:197], v[110:113]
	v_mfma_f32_16x16x32_bf16 v[94:97], v[132:135], v[198:201], v[94:97]
	v_mfma_f32_16x16x32_bf16 v[94:97], v[144:147], v[202:205], v[94:97]
	v_mfma_f32_16x16x32_bf16 v[78:81], v[132:135], v[206:209], v[78:81]
	v_mfma_f32_16x16x32_bf16 v[78:81], v[144:147], v[210:213], v[78:81]
	v_mfma_f32_16x16x32_bf16 v[122:125], v[158:161], v[182:185], v[122:125]
	v_mfma_f32_16x16x32_bf16 v[122:125], v[162:165], v[186:189], v[122:125]
	v_mfma_f32_16x16x32_bf16 v[106:109], v[158:161], v[190:193], v[106:109]
	v_mfma_f32_16x16x32_bf16 v[106:109], v[162:165], v[194:197], v[106:109]
	v_mfma_f32_16x16x32_bf16 v[90:93], v[158:161], v[198:201], v[90:93]
	v_mfma_f32_16x16x32_bf16 v[90:93], v[162:165], v[202:205], v[90:93]
	v_mfma_f32_16x16x32_bf16 v[74:77], v[158:161], v[206:209], v[74:77]
	v_mfma_f32_16x16x32_bf16 v[74:77], v[162:165], v[210:213], v[74:77]
	v_mfma_f32_16x16x32_bf16 v[118:121], v[166:169], v[182:185], v[118:121]
	v_mfma_f32_16x16x32_bf16 v[118:121], v[170:173], v[186:189], v[118:121]
	v_mfma_f32_16x16x32_bf16 v[102:105], v[166:169], v[190:193], v[102:105]
	v_mfma_f32_16x16x32_bf16 v[102:105], v[170:173], v[194:197], v[102:105]
	v_mfma_f32_16x16x32_bf16 v[86:89], v[166:169], v[198:201], v[86:89]
	v_mfma_f32_16x16x32_bf16 v[86:89], v[170:173], v[202:205], v[86:89]
	v_mfma_f32_16x16x32_bf16 v[70:73], v[166:169], v[206:209], v[70:73]
	v_mfma_f32_16x16x32_bf16 v[70:73], v[170:173], v[210:213], v[70:73]
	v_mfma_f32_16x16x32_bf16 v[114:117], v[174:177], v[182:185], v[114:117]
	v_mfma_f32_16x16x32_bf16 v[114:117], v[178:181], v[186:189], v[114:117]
	v_mfma_f32_16x16x32_bf16 v[98:101], v[174:177], v[190:193], v[98:101]
	v_mfma_f32_16x16x32_bf16 v[98:101], v[178:181], v[194:197], v[98:101]
	v_mfma_f32_16x16x32_bf16 v[82:85], v[174:177], v[198:201], v[82:85]
	v_mfma_f32_16x16x32_bf16 v[82:85], v[178:181], v[202:205], v[82:85]
	v_mfma_f32_16x16x32_bf16 v[66:69], v[174:177], v[206:209], v[66:69]
	v_mfma_f32_16x16x32_bf16 v[66:69], v[178:181], v[210:213], v[66:69]
	s_setprio 0
	s_barrier
	s_mov_b32 m0, s64
	s_mov_b32 s39, s31
	ds_read_b128 v[182:185], v156 offset:16384
	ds_read_b128 v[186:189], v156 offset:17408
	buffer_load_dwordx4 v152, s[36:39], s48 offen lds
	s_mov_b32 m0, s65
	ds_read_b128 v[190:193], v156 offset:18432
	ds_read_b128 v[194:197], v156 offset:19456
	buffer_load_dwordx4 v154, s[36:39], s48 offen lds
	s_add_i32 s51, s48, 0x160000
	s_mov_b32 m0, s66
	ds_read_b128 v[198:201], v156 offset:20480
	ds_read_b128 v[202:205], v156 offset:21504
	buffer_load_dwordx4 v152, s[36:39], s51 offen lds
	s_mov_b32 m0, s67
	ds_read_b128 v[206:209], v156 offset:22528
	ds_read_b128 v[210:213], v156 offset:23552
	buffer_load_dwordx4 v154, s[36:39], s51 offen lds
	s_waitcnt vmcnt(6)
	s_waitcnt lgkmcnt(0)
	s_barrier
	s_setprio 1
	s_waitcnt lgkmcnt(0)
	v_mfma_f32_16x16x32_bf16 v[62:65], v[132:135], v[182:185], v[62:65]
	v_mfma_f32_16x16x32_bf16 v[62:65], v[144:147], v[186:189], v[62:65]
	v_mfma_f32_16x16x32_bf16 v[46:49], v[132:135], v[190:193], v[46:49]
	v_mfma_f32_16x16x32_bf16 v[46:49], v[144:147], v[194:197], v[46:49]
	v_mfma_f32_16x16x32_bf16 v[30:33], v[132:135], v[198:201], v[30:33]
	v_mfma_f32_16x16x32_bf16 v[30:33], v[144:147], v[202:205], v[30:33]
	v_mfma_f32_16x16x32_bf16 v[14:17], v[132:135], v[206:209], v[14:17]
	v_mfma_f32_16x16x32_bf16 v[14:17], v[144:147], v[210:213], v[14:17]
	v_mfma_f32_16x16x32_bf16 v[58:61], v[158:161], v[182:185], v[58:61]
	v_mfma_f32_16x16x32_bf16 v[58:61], v[162:165], v[186:189], v[58:61]
	v_mfma_f32_16x16x32_bf16 v[42:45], v[158:161], v[190:193], v[42:45]
	v_mfma_f32_16x16x32_bf16 v[42:45], v[162:165], v[194:197], v[42:45]
	v_mfma_f32_16x16x32_bf16 v[26:29], v[158:161], v[198:201], v[26:29]
	v_mfma_f32_16x16x32_bf16 v[26:29], v[162:165], v[202:205], v[26:29]
	v_mfma_f32_16x16x32_bf16 v[10:13], v[158:161], v[206:209], v[10:13]
	v_mfma_f32_16x16x32_bf16 v[10:13], v[162:165], v[210:213], v[10:13]
	v_mfma_f32_16x16x32_bf16 v[54:57], v[166:169], v[182:185], v[54:57]
	v_mfma_f32_16x16x32_bf16 v[54:57], v[170:173], v[186:189], v[54:57]
	v_mfma_f32_16x16x32_bf16 v[38:41], v[166:169], v[190:193], v[38:41]
	v_mfma_f32_16x16x32_bf16 v[38:41], v[170:173], v[194:197], v[38:41]
	v_mfma_f32_16x16x32_bf16 v[22:25], v[166:169], v[198:201], v[22:25]
	v_mfma_f32_16x16x32_bf16 v[22:25], v[170:173], v[202:205], v[22:25]
	v_mfma_f32_16x16x32_bf16 v[6:9], v[166:169], v[206:209], v[6:9]
	v_mfma_f32_16x16x32_bf16 v[6:9], v[170:173], v[210:213], v[6:9]
	v_mfma_f32_16x16x32_bf16 v[50:53], v[174:177], v[182:185], v[50:53]
	v_mfma_f32_16x16x32_bf16 v[50:53], v[178:181], v[186:189], v[50:53]
	v_mfma_f32_16x16x32_bf16 v[34:37], v[174:177], v[190:193], v[34:37]
	v_mfma_f32_16x16x32_bf16 v[34:37], v[178:181], v[194:197], v[34:37]
	v_mfma_f32_16x16x32_bf16 v[18:21], v[174:177], v[198:201], v[18:21]
	v_mfma_f32_16x16x32_bf16 v[18:21], v[178:181], v[202:205], v[18:21]
	v_mfma_f32_16x16x32_bf16 v[2:5], v[174:177], v[206:209], v[2:5]
	v_mfma_f32_16x16x32_bf16 v[2:5], v[178:181], v[210:213], v[2:5]
	s_setprio 0
	s_barrier
	v_add_u32_e32 v130, 0x18000, v155
	ds_read_b128 v[132:135], v130
	ds_read_b128 v[144:147], v130 offset:1024
	ds_read_b128 v[158:161], v130 offset:2048
	ds_read_b128 v[162:165], v130 offset:3072
	v_add_u32_e32 v130, 0x1c000, v155
	ds_read_b128 v[166:169], v130
	ds_read_b128 v[170:173], v130 offset:1024
	ds_read_b128 v[174:177], v130 offset:2048
	ds_read_b128 v[178:181], v130 offset:3072
	s_mov_b32 m0, s62
	ds_read_b128 v[182:185], v156 offset:32768
	ds_read_b128 v[186:189], v156 offset:33792
	buffer_load_dwordx4 v151, s[28:31], s50 offen lds
	s_mov_b32 m0, s68
	ds_read_b128 v[190:193], v156 offset:34816
	ds_read_b128 v[194:197], v156 offset:35840
	buffer_load_dwordx4 v153, s[28:31], s50 offen lds
	s_add_i32 s50, s50, 0x160000
	s_mov_b32 m0, s69
	ds_read_b128 v[198:201], v156 offset:36864
	ds_read_b128 v[202:205], v156 offset:37888
	buffer_load_dwordx4 v151, s[28:31], s50 offen lds
	s_mov_b32 m0, s70
	ds_read_b128 v[206:209], v156 offset:38912
	ds_read_b128 v[210:213], v156 offset:39936
	buffer_load_dwordx4 v153, s[28:31], s50 offen lds
	s_waitcnt vmcnt(8)
	s_waitcnt lgkmcnt(0)
	s_barrier
	s_setprio 1
	s_waitcnt lgkmcnt(0)
	v_mfma_f32_16x16x32_bf16 v[126:129], v[132:135], v[182:185], v[126:129]
	v_mfma_f32_16x16x32_bf16 v[126:129], v[144:147], v[186:189], v[126:129]
	v_mfma_f32_16x16x32_bf16 v[110:113], v[132:135], v[190:193], v[110:113]
	v_mfma_f32_16x16x32_bf16 v[110:113], v[144:147], v[194:197], v[110:113]
	v_mfma_f32_16x16x32_bf16 v[94:97], v[132:135], v[198:201], v[94:97]
	v_mfma_f32_16x16x32_bf16 v[94:97], v[144:147], v[202:205], v[94:97]
	v_mfma_f32_16x16x32_bf16 v[78:81], v[132:135], v[206:209], v[78:81]
	v_mfma_f32_16x16x32_bf16 v[78:81], v[144:147], v[210:213], v[78:81]
	v_mfma_f32_16x16x32_bf16 v[122:125], v[158:161], v[182:185], v[122:125]
	v_mfma_f32_16x16x32_bf16 v[122:125], v[162:165], v[186:189], v[122:125]
	v_mfma_f32_16x16x32_bf16 v[106:109], v[158:161], v[190:193], v[106:109]
	v_mfma_f32_16x16x32_bf16 v[106:109], v[162:165], v[194:197], v[106:109]
	v_mfma_f32_16x16x32_bf16 v[90:93], v[158:161], v[198:201], v[90:93]
	v_mfma_f32_16x16x32_bf16 v[90:93], v[162:165], v[202:205], v[90:93]
	v_mfma_f32_16x16x32_bf16 v[74:77], v[158:161], v[206:209], v[74:77]
	v_mfma_f32_16x16x32_bf16 v[74:77], v[162:165], v[210:213], v[74:77]
	v_mfma_f32_16x16x32_bf16 v[118:121], v[166:169], v[182:185], v[118:121]
	v_mfma_f32_16x16x32_bf16 v[118:121], v[170:173], v[186:189], v[118:121]
	v_mfma_f32_16x16x32_bf16 v[102:105], v[166:169], v[190:193], v[102:105]
	v_mfma_f32_16x16x32_bf16 v[102:105], v[170:173], v[194:197], v[102:105]
	v_mfma_f32_16x16x32_bf16 v[86:89], v[166:169], v[198:201], v[86:89]
	v_mfma_f32_16x16x32_bf16 v[86:89], v[170:173], v[202:205], v[86:89]
	v_mfma_f32_16x16x32_bf16 v[70:73], v[166:169], v[206:209], v[70:73]
	v_mfma_f32_16x16x32_bf16 v[70:73], v[170:173], v[210:213], v[70:73]
	v_mfma_f32_16x16x32_bf16 v[114:117], v[174:177], v[182:185], v[114:117]
	v_mfma_f32_16x16x32_bf16 v[114:117], v[178:181], v[186:189], v[114:117]
	v_mfma_f32_16x16x32_bf16 v[98:101], v[174:177], v[190:193], v[98:101]
	v_mfma_f32_16x16x32_bf16 v[98:101], v[178:181], v[194:197], v[98:101]
	v_mfma_f32_16x16x32_bf16 v[82:85], v[174:177], v[198:201], v[82:85]
	v_mfma_f32_16x16x32_bf16 v[82:85], v[178:181], v[202:205], v[82:85]
	v_mfma_f32_16x16x32_bf16 v[66:69], v[174:177], v[206:209], v[66:69]
	v_mfma_f32_16x16x32_bf16 v[66:69], v[178:181], v[210:213], v[66:69]
	s_setprio 0
	s_barrier
	s_mov_b32 m0, s72
	ds_read_b128 v[182:185], v156 offset:49152
	ds_read_b128 v[186:189], v156 offset:50176
	buffer_load_dwordx4 v152, s[36:39], s49 offen lds
	s_mov_b32 m0, s73
	ds_read_b128 v[190:193], v156 offset:51200
	ds_read_b128 v[194:197], v156 offset:52224
	buffer_load_dwordx4 v154, s[36:39], s49 offen lds
	s_add_i32 s48, s48, 0x160080
	s_mov_b32 m0, s74
	ds_read_b128 v[198:201], v156 offset:53248
	ds_read_b128 v[202:205], v156 offset:54272
	buffer_load_dwordx4 v152, s[36:39], s48 offen lds
	s_mov_b32 m0, s75
	ds_read_b128 v[206:209], v156 offset:55296
	ds_read_b128 v[210:213], v156 offset:56320
	buffer_load_dwordx4 v154, s[36:39], s48 offen lds
	s_waitcnt vmcnt(6)
	s_waitcnt lgkmcnt(0)
	s_barrier
	s_setprio 1
	s_waitcnt lgkmcnt(0)
	v_mfma_f32_16x16x32_bf16 v[62:65], v[132:135], v[182:185], v[62:65]
	v_mfma_f32_16x16x32_bf16 v[62:65], v[144:147], v[186:189], v[62:65]
	v_mfma_f32_16x16x32_bf16 v[46:49], v[132:135], v[190:193], v[46:49]
	v_mfma_f32_16x16x32_bf16 v[46:49], v[144:147], v[194:197], v[46:49]
	v_mfma_f32_16x16x32_bf16 v[30:33], v[132:135], v[198:201], v[30:33]
	v_mfma_f32_16x16x32_bf16 v[30:33], v[144:147], v[202:205], v[30:33]
	v_mfma_f32_16x16x32_bf16 v[14:17], v[132:135], v[206:209], v[14:17]
	v_mfma_f32_16x16x32_bf16 v[14:17], v[144:147], v[210:213], v[14:17]
	v_mfma_f32_16x16x32_bf16 v[58:61], v[158:161], v[182:185], v[58:61]
	v_mfma_f32_16x16x32_bf16 v[58:61], v[162:165], v[186:189], v[58:61]
	v_mfma_f32_16x16x32_bf16 v[42:45], v[158:161], v[190:193], v[42:45]
	v_mfma_f32_16x16x32_bf16 v[42:45], v[162:165], v[194:197], v[42:45]
	v_mfma_f32_16x16x32_bf16 v[26:29], v[158:161], v[198:201], v[26:29]
	v_mfma_f32_16x16x32_bf16 v[26:29], v[162:165], v[202:205], v[26:29]
	v_mfma_f32_16x16x32_bf16 v[10:13], v[158:161], v[206:209], v[10:13]
	v_mfma_f32_16x16x32_bf16 v[10:13], v[162:165], v[210:213], v[10:13]
	v_mfma_f32_16x16x32_bf16 v[54:57], v[166:169], v[182:185], v[54:57]
	v_mfma_f32_16x16x32_bf16 v[54:57], v[170:173], v[186:189], v[54:57]
	v_mfma_f32_16x16x32_bf16 v[38:41], v[166:169], v[190:193], v[38:41]
	v_mfma_f32_16x16x32_bf16 v[38:41], v[170:173], v[194:197], v[38:41]
	v_mfma_f32_16x16x32_bf16 v[22:25], v[166:169], v[198:201], v[22:25]
	v_mfma_f32_16x16x32_bf16 v[22:25], v[170:173], v[202:205], v[22:25]
	v_mfma_f32_16x16x32_bf16 v[6:9], v[166:169], v[206:209], v[6:9]
	v_mfma_f32_16x16x32_bf16 v[6:9], v[170:173], v[210:213], v[6:9]
	v_mfma_f32_16x16x32_bf16 v[50:53], v[174:177], v[182:185], v[50:53]
	v_mfma_f32_16x16x32_bf16 v[50:53], v[178:181], v[186:189], v[50:53]
	v_mfma_f32_16x16x32_bf16 v[34:37], v[174:177], v[190:193], v[34:37]
	v_mfma_f32_16x16x32_bf16 v[34:37], v[178:181], v[194:197], v[34:37]
	v_mfma_f32_16x16x32_bf16 v[18:21], v[174:177], v[198:201], v[18:21]
	v_mfma_f32_16x16x32_bf16 v[18:21], v[178:181], v[202:205], v[18:21]
	v_mfma_f32_16x16x32_bf16 v[2:5], v[174:177], v[206:209], v[2:5]
	v_mfma_f32_16x16x32_bf16 v[2:5], v[178:181], v[210:213], v[2:5]
	s_setprio 0
	s_barrier
	s_add_i32 s39, s92, 2
	s_cmpk_gt_u32 s92, 0x55
	s_cbranch_scc1 .LBB0_1005
	s_mov_b32 s92, s39
	s_branch .LBB0_999
